# v7: v6 + dropped the s_nop 0 hipcc pads between inline-asm v_max3 (plain VALU->VALU dependency, no hazard)
# speedup vs baseline: 1.0127x; 1.0029x over previous
; __device__ __forceinline__ float max3f(float a, float b, float c) { float r; asm("v_max3_f32 %0, %1, %2, %3" : "=v"(r) : "v"(a), "v"(b), "v"(c)); return r; }
; template <int DQK, int DV, bool BIAS> ...
;     ...
;         if (BIAS) {
;             asm volatile("s_nop 15\n\ts_nop 7" : "+v"(p0), "+v"(p1));
;             const float d0 = qp - (float)(t * 64 + 4 * hi);
; #pragma unroll
;             for (int r = 0; r < 16; ++r) { const float dk = d0 - (float)((r & 3) + 8 * (r >> 2)); p0[r] = p0[r] - sl2 * fabsf(dk); p1[r] = p1[r] - sl2 * fabsf(dk - 32.f); }
;         } else {
;             asm volatile("s_nop 15\n\ts_nop 7" : "+v"(p0), "+v"(p1));
;         }
;         float mxa = max3f(p0[0], p0[1], p1[0]), mxb = max3f(p0[2], p0[3], p1[1]); mxa = max3f(mxa, p1[2], p1[3]);
; #pragma unroll
;         for (int r = 4; r < 16; r += 4) { mxa = max3f(mxa, p0[r], p0[r + 1]); mxb = max3f(mxb, p0[r + 2], p0[r + 3]); mxa = max3f(mxa, p1[r], p1[r + 1]); mxb = max3f(mxb, p1[r + 2], p1[r + 3]); }
;         float mx = fmaxf(mxa, mxb);
;         if (__any(mx > 8.f)) {
.LBB0_578:
	ds_read_b128 v[82:85], v175
	ds_read_b128 v[152:155], v175 offset:32
	ds_read_b128 v[156:159], v175 offset:4608
	ds_read_b128 v[160:163], v175 offset:4640
	v_cvt_f32_u32_e32 v150, v173
	s_waitcnt lgkmcnt(3)
	v_mfma_f32_32x32x16_bf16 v[98:113], v[82:85], v[114:117], v[66:81]
	v_sub_f32_e32 v178, v172, v150
	v_add_f32_e32 v179, -1.0, v178
	s_waitcnt lgkmcnt(1)
	v_mfma_f32_32x32x16_bf16 v[82:97], v[156:159], v[114:117], v[66:81]
	v_mfma_f32_32x32x16_bf16 v[98:113], v[152:155], v[118:121], v[98:113]
	ds_read_b128 v[152:155], v175 offset:64
	ds_read_b128 v[156:159], v175 offset:96
	s_waitcnt lgkmcnt(2)
	v_mfma_f32_32x32x16_bf16 v[82:97], v[160:163], v[118:121], v[82:97]
	s_waitcnt lgkmcnt(1)
	v_mfma_f32_32x32x16_bf16 v[98:113], v[152:155], v[122:125], v[98:113]
	ds_read_b128 v[152:155], v175 offset:4672
	ds_read_b128 v[160:163], v175 offset:4704
	s_waitcnt lgkmcnt(1)
	v_mfma_f32_32x32x16_bf16 v[82:97], v[152:155], v[122:125], v[82:97]
	v_and_b32_e32 v152, 0x7fffffff, v178
	v_and_b32_e32 v153, 0x7fffffff, v179
	v_mfma_f32_32x32x16_bf16 v[98:113], v[156:159], v[126:129], v[98:113]
	s_waitcnt lgkmcnt(0)
	v_mfma_f32_32x32x16_bf16 v[82:97], v[160:163], v[126:129], v[82:97]
	s_nop 15
	s_nop 7
	s_nop 9
	v_pk_fma_f32 v[156:157], v[142:143], v[152:153], v[98:99] neg_lo:[1,0,0] neg_hi:[1,0,0]
	v_pk_add_f32 v[98:99], v[178:179], s[8:9] op_sel_hi:[1,0]
	s_nop 0
	v_fma_f32 v99, -v143, |v99|, v83
	v_fma_f32 v98, -v142, |v98|, v82
	v_pk_add_f32 v[82:83], v[178:179], s[10:11] op_sel_hi:[0,1]
	v_fma_f32 v161, -v143, |v83|, v101
	v_fma_f32 v160, -v142, |v82|, v100
	v_pk_add_f32 v[82:83], v[82:83], s[8:9] op_sel_hi:[1,0]
	v_fma_f32 v153, -v143, |v83|, v85
	v_fma_f32 v152, -v142, |v82|, v84
	v_pk_add_f32 v[82:83], v[178:179], s[22:23] op_sel_hi:[0,1]
	v_fma_f32 v165, -v143, |v83|, v103
	v_fma_f32 v164, -v142, |v82|, v102
	v_pk_add_f32 v[82:83], v[82:83], s[8:9] op_sel_hi:[1,0]
	v_fma_f32 v103, -v143, |v83|, v87
	v_fma_f32 v102, -v142, |v82|, v86
	v_pk_add_f32 v[82:83], v[178:179], s[34:35] op_sel_hi:[0,1]
	v_fma_f32 v167, -v143, |v83|, v105
	v_fma_f32 v166, -v142, |v82|, v104
	v_pk_add_f32 v[82:83], v[82:83], s[8:9] op_sel_hi:[1,0]
	v_fma_f32 v155, -v143, |v83|, v89
	v_fma_f32 v154, -v142, |v82|, v88
	v_pk_add_f32 v[82:83], v[178:179], s[36:37] op_sel_hi:[0,1]
	v_fma_f32 v159, -v143, |v83|, v107
	v_fma_f32 v158, -v142, |v82|, v106
	v_pk_add_f32 v[82:83], v[82:83], s[8:9] op_sel_hi:[1,0]
	v_fma_f32 v101, -v143, |v83|, v91
	v_fma_f32 v100, -v142, |v82|, v90
	v_pk_add_f32 v[82:83], v[178:179], s[38:39] op_sel_hi:[0,1]
	v_fma_f32 v163, -v143, |v83|, v109
	v_fma_f32 v162, -v142, |v82|, v108
	v_pk_add_f32 v[82:83], v[82:83], s[8:9] op_sel_hi:[1,0]
	v_fma_f32 v105, -v143, |v83|, v93
	v_fma_f32 v104, -v142, |v82|, v92
	v_pk_add_f32 v[82:83], v[178:179], s[40:41] op_sel_hi:[0,1]
	v_fma_f32 v111, -v143, |v83|, v111
	v_fma_f32 v110, -v142, |v82|, v110
	v_pk_add_f32 v[82:83], v[82:83], s[8:9] op_sel_hi:[1,0]
	v_fma_f32 v107, -v143, |v83|, v95
	v_fma_f32 v106, -v142, |v82|, v94
	v_pk_add_f32 v[82:83], v[178:179], s[42:43] op_sel_hi:[0,1]
	v_fma_f32 v113, -v143, |v83|, v113
	v_fma_f32 v112, -v142, |v82|, v112
	v_pk_add_f32 v[82:83], v[82:83], s[8:9] op_sel_hi:[1,0]
	v_fma_f32 v109, -v143, |v83|, v97
	v_fma_f32 v108, -v142, |v82|, v96
	v_max3_f32 v82, v156, v157, v98
	v_max3_f32 v83, v160, v161, v99
	v_max3_f32 v82, v82, v152, v153
	v_max3_f32 v83, v83, v166, v167
	v_max3_f32 v82, v82, v164, v165
	v_max3_f32 v83, v83, v154, v155
	v_max3_f32 v82, v82, v102, v103
	v_max3_f32 v83, v83, v162, v163
	v_max3_f32 v82, v82, v158, v159
	v_max3_f32 v83, v83, v104, v105
	v_max3_f32 v82, v82, v100, v101
	v_max3_f32 v83, v83, v112, v113
	v_max3_f32 v82, v82, v110, v111
	v_max3_f32 v83, v83, v108, v109
	v_max3_f32 v82, v82, v106, v107
	v_max_f32_e32 v83, v83, v83
	v_max_f32_e32 v82, v82, v82
	v_max_f32_e32 v82, v82, v83
	v_cmp_lt_f32_e32 vcc, s52, v82
	s_cbranch_vccz .LBB0_580
; template <int DQK, int DV, bool BIAS> ...
;     ...
;         if (__any(mx > 8.f)) {
;             mx = fmaxf(mx, __shfl_xor(mx, 32));
;             const float dl = fmaxf(mx, 0.f); mhat += dl;
;             const float f = __builtin_amdgcn_exp2f(-dl);
; #pragma unroll
;             for (int r = 0; r < 16; ++r) { p0[r] -= dl; p1[r] -= dl; negm[r] = -mhat; }
;             l *= f;
; #pragma unroll
;             for (int d = 0; d < NDT; ++d)
; #pragma unroll
;                 for (int r = 0; r < 16; ++r) o[d][r] *= f;
;         }
	v_and_b32_e32 v67, 64, v170
	v_xor_b32_e32 v66, 32, v170
	v_add_u32_e32 v67, 64, v67
	v_cmp_lt_i32_e32 vcc, v66, v67
	s_nop 1
	v_cndmask_b32_e32 v66, v170, v66, vcc
	v_lshlrev_b32_e32 v66, 2, v66
	ds_bpermute_b32 v66, v66, v82
	s_waitcnt lgkmcnt(0)
	v_max3_f32 v67, v82, v66, 0
	v_exp_f32_e64 v66, -v67
	v_add_f32_e32 v176, v176, v67
	v_xor_b32_e32 v82, 0x80000000, v176
	v_sub_f32_e32 v98, v98, v67
	v_sub_f32_e32 v99, v99, v67
	v_sub_f32_e32 v152, v152, v67
	v_sub_f32_e32 v153, v153, v67
	v_sub_f32_e32 v102, v102, v67
	v_sub_f32_e32 v103, v103, v67
	v_sub_f32_e32 v154, v154, v67
	v_sub_f32_e32 v155, v155, v67
	v_sub_f32_e32 v100, v100, v67
	v_sub_f32_e32 v101, v101, v67
	v_sub_f32_e32 v104, v104, v67
	v_sub_f32_e32 v105, v105, v67
	v_sub_f32_e32 v106, v106, v67
	v_sub_f32_e32 v107, v107, v67
	v_sub_f32_e32 v108, v108, v67
	v_sub_f32_e32 v109, v109, v67
	v_pk_mul_f32 v[64:65], v[64:65], v[66:67] op_sel_hi:[1,0]
	v_pk_mul_f32 v[62:63], v[62:63], v[66:67] op_sel_hi:[1,0]
	v_pk_mul_f32 v[60:61], v[60:61], v[66:67] op_sel_hi:[1,0]
	v_pk_mul_f32 v[58:59], v[58:59], v[66:67] op_sel_hi:[1,0]
	v_pk_mul_f32 v[56:57], v[56:57], v[66:67] op_sel_hi:[1,0]
	v_pk_mul_f32 v[54:55], v[54:55], v[66:67] op_sel_hi:[1,0]
	v_pk_mul_f32 v[52:53], v[52:53], v[66:67] op_sel_hi:[1,0]
	v_pk_mul_f32 v[50:51], v[50:51], v[66:67] op_sel_hi:[1,0]
	v_pk_mul_f32 v[48:49], v[48:49], v[66:67] op_sel_hi:[1,0]
	v_pk_mul_f32 v[46:47], v[46:47], v[66:67] op_sel_hi:[1,0]
	v_pk_mul_f32 v[44:45], v[44:45], v[66:67] op_sel_hi:[1,0]
	v_pk_mul_f32 v[42:43], v[42:43], v[66:67] op_sel_hi:[1,0]
	v_pk_mul_f32 v[40:41], v[40:41], v[66:67] op_sel_hi:[1,0]
	v_pk_mul_f32 v[38:39], v[38:39], v[66:67] op_sel_hi:[1,0]
	v_pk_mul_f32 v[36:37], v[36:37], v[66:67] op_sel_hi:[1,0]
	v_pk_mul_f32 v[34:35], v[34:35], v[66:67] op_sel_hi:[1,0]
	v_pk_mul_f32 v[32:33], v[32:33], v[66:67] op_sel_hi:[1,0]
	v_pk_mul_f32 v[30:31], v[30:31], v[66:67] op_sel_hi:[1,0]
	v_pk_mul_f32 v[28:29], v[28:29], v[66:67] op_sel_hi:[1,0]
	v_pk_mul_f32 v[26:27], v[26:27], v[66:67] op_sel_hi:[1,0]
	v_pk_mul_f32 v[24:25], v[24:25], v[66:67] op_sel_hi:[1,0]
	v_pk_mul_f32 v[22:23], v[22:23], v[66:67] op_sel_hi:[1,0]
	v_pk_mul_f32 v[20:21], v[20:21], v[66:67] op_sel_hi:[1,0]
	v_pk_mul_f32 v[18:19], v[18:19], v[66:67] op_sel_hi:[1,0]
	v_pk_mul_f32 v[16:17], v[16:17], v[66:67] op_sel_hi:[1,0]
	v_pk_mul_f32 v[14:15], v[14:15], v[66:67] op_sel_hi:[1,0]
	v_pk_mul_f32 v[12:13], v[12:13], v[66:67] op_sel_hi:[1,0]
	v_pk_mul_f32 v[10:11], v[10:11], v[66:67] op_sel_hi:[1,0]
	v_pk_mul_f32 v[8:9], v[8:9], v[66:67] op_sel_hi:[1,0]
	v_pk_mul_f32 v[6:7], v[6:7], v[66:67] op_sel_hi:[1,0]
	v_pk_mul_f32 v[4:5], v[4:5], v[66:67] op_sel_hi:[1,0]
	v_pk_mul_f32 v[2:3], v[2:3], v[66:67] op_sel_hi:[1,0]
	v_sub_f32_e32 v156, v156, v67
	v_sub_f32_e32 v157, v157, v67
	v_sub_f32_e32 v160, v160, v67
	v_sub_f32_e32 v161, v161, v67
	v_sub_f32_e32 v164, v164, v67
	v_sub_f32_e32 v165, v165, v67
	v_sub_f32_e32 v166, v166, v67
	v_sub_f32_e32 v167, v167, v67
	v_sub_f32_e32 v158, v158, v67
	v_sub_f32_e32 v159, v159, v67
	v_sub_f32_e32 v162, v162, v67
	v_sub_f32_e32 v163, v163, v67
	v_sub_f32_e32 v110, v110, v67
	v_sub_f32_e32 v111, v111, v67
	v_sub_f32_e32 v112, v112, v67
	v_sub_f32_e32 v113, v113, v67
	v_mul_f32_e32 v151, v151, v66
	v_mov_b32_e32 v83, v82
	v_mov_b32_e32 v84, v82
	v_mov_b32_e32 v85, v82
	v_mov_b32_e32 v86, v82
	v_mov_b32_e32 v87, v82
	v_mov_b32_e32 v88, v82
	v_mov_b32_e32 v89, v82
	v_mov_b32_e32 v90, v82
	v_mov_b32_e32 v91, v82
	v_mov_b32_e32 v92, v82
	v_mov_b32_e32 v93, v82
	v_mov_b32_e32 v94, v82
	v_mov_b32_e32 v95, v82
	v_mov_b32_e32 v96, v82
	v_mov_b32_e32 v97, v82
	v_mov_b32_e32 v66, v82
	v_mov_b32_e32 v67, v82
	v_mov_b32_e32 v68, v82
	v_mov_b32_e32 v69, v82
	v_mov_b32_e32 v70, v82
	v_mov_b32_e32 v71, v82
	v_mov_b32_e32 v72, v82
	v_mov_b32_e32 v73, v82
	v_mov_b32_e32 v74, v82
	v_mov_b32_e32 v75, v82
	v_mov_b32_e32 v76, v82
	v_mov_b32_e32 v77, v82
	v_mov_b32_e32 v78, v82
	v_mov_b32_e32 v79, v82
	v_mov_b32_e32 v80, v82
	v_mov_b32_e32 v81, v82
	s_branch .LBB0_581

; template <int DQK, int DV, bool BIAS> ...
;     ...
;         const LAS unsigned char* kb = lds + buf * KBUF + r32 * KP + hi * 16;
; #pragma unroll
;         for (int ks = 0; ks < NKS; ++ks) {
;             const bf16x8 k0 = *(const LAS bf16x8*)(kb + ks * 32), k1 = *(const LAS bf16x8*)(kb + 32 * KP + ks * 32);
;             if (ks == 0) { p0 = __builtin_amdgcn_mfma_f32_32x32x16_bf16(k0, qf[0], negm, 0, 0, 0); p1 = __builtin_amdgcn_mfma_f32_32x32x16_bf16(k1, qf[0], negm, 0, 0, 0); }
;             else { p0 = __builtin_amdgcn_mfma_f32_32x32x16_bf16(k0, qf[ks], p0, 0, 0, 0); p1 = __builtin_amdgcn_mfma_f32_32x32x16_bf16(k1, qf[ks], p1, 0, 0, 0); }
;         }
;         if (BIAS) {
;             asm volatile("s_nop 15\n\ts_nop 7" : "+v"(p0), "+v"(p1));
;             const float d0 = qp - (float)(t * 64 + 4 * hi);
; #pragma unroll
;             for (int r = 0; r < 16; ++r) { const float dk = d0 - (float)((r & 3) + 8 * (r >> 2)); p0[r] = p0[r] - sl2 * fabsf(dk); p1[r] = p1[r] - sl2 * fabsf(dk - 32.f); }
;         } else {
;             asm volatile("s_nop 15\n\ts_nop 7" : "+v"(p0), "+v"(p1));
;         }
;         float mxa = max3f(p0[0], p0[1], p1[0]), mxb = max3f(p0[2], p0[3], p1[1]); mxa = max3f(mxa, p1[2], p1[3]);
; #pragma unroll
;         for (int r = 4; r < 16; r += 4) { mxa = max3f(mxa, p0[r], p0[r + 1]); mxb = max3f(mxb, p0[r + 2], p0[r + 3]); mxa = max3f(mxa, p1[r], p1[r + 1]); mxb = max3f(mxb, p1[r + 2], p1[r + 3]); }
;         float mx = fmaxf(mxa, mxb);
;         if (__any(mx > 8.f)) {
;     ...
;                 for (int j = 0; j < 8; ++j) { e[j] = __builtin_amdgcn_exp2f(hs < 2 ? p0[8 * (hs & 1) + j] : p1[8 * (hs & 1) + j]); ls += e[j]; }
;                 pw[hs].x = cvtpk(e[0], e[1]); pw[hs].y = cvtpk(e[2], e[3]); pw[hs].z = cvtpk(e[4], e[5]); pw[hs].w = cvtpk(e[6], e[7]);
;                 const bf16x8 pbv = __builtin_bit_cast(bf16x8, pw[hs]);
; #pragma unroll
;                 for (int d = 0; d < NDT; ++d) { const LAS unsigned char* vp = vbase + d * 4096 + hs * 1024;
;                     const v4i16_t a0 = __builtin_amdgcn_ds_read_tr16_b64_v4i16((LAS v4i16_t*)vp), a1 = __builtin_amdgcn_ds_read_tr16_b64_v4i16((LAS v4i16_t*)(vp + 512));
;                     const bf16x8 av = {a0[0], a0[1], a0[2], a0[3], a1[0], a1[1], a1[2], a1[3]};
;                     o[d] = __builtin_amdgcn_mfma_f32_32x32x16_bf16(av, pbv, o[d], 0, 0, 0); }
.LBB0_584:
	ds_read_b128 v[192:195], v175 offset:9216
	ds_read_b128 v[196:199], v175 offset:9248
	v_add_f32_e32 v156, 0, v156
	v_add_f32_e32 v156, v157, v156
	v_add_f32_e32 v156, v160, v156
	s_waitcnt lgkmcnt(1)
	v_mfma_f32_32x32x16_bf16 v[98:113], v[192:195], v[114:117], v[82:97]
	ds_read_b128 v[192:195], v175 offset:13824
	ds_read_b128 v[200:203], v175 offset:13856
	v_add_f32_e32 v156, v161, v156
	v_add_f32_e32 v156, v164, v156
	v_add_f32_e32 v150, v150, v156
	v_add_f32_e32 v150, v165, v150
	v_add_f32_e32 v150, v166, v150
	v_add_f32_e32 v150, v167, v150
	s_waitcnt lgkmcnt(1)
	v_mfma_f32_32x32x16_bf16 v[82:97], v[192:195], v[114:117], v[82:97]
	v_add_f32_e32 v150, v177, v150
	v_add_f32_e32 v150, v178, v150
	v_add_f32_e32 v150, v158, v150
	v_add_f32_e32 v150, v159, v150
	ds_read_b128 v[164:167], v175 offset:9280
	v_add_f32_e32 v150, v162, v150
	v_add_f32_e32 v150, v163, v150
	v_mfma_f32_32x32x16_bf16 v[98:113], v[196:199], v[118:121], v[98:113]
	v_add_f32_e32 v150, v179, v150
	v_add_f32_e32 v150, v180, v150
	v_add_f32_e32 v150, v181, v150
	v_add_f32_e32 v150, v152, v150
	ds_read_b128 v[156:159], v175 offset:13888
	ds_read_b128 v[160:163], v175 offset:9312
	v_add_f32_e32 v150, v153, v150
	v_add_f32_e32 v150, v182, v150
	s_waitcnt lgkmcnt(3)
	v_mfma_f32_32x32x16_bf16 v[82:97], v[200:203], v[118:121], v[82:97]
	v_add_f32_e32 v150, v183, v150
	v_add_f32_e32 v150, v154, v150
	v_add_f32_e32 v150, v155, v150
	v_add_f32_e32 v150, v184, v150
	v_add_f32_e32 v150, v185, v150
	v_add_u32_e32 v152, 64, v173
	v_add_f32_e32 v150, v186, v150
	s_waitcnt lgkmcnt(2)
	v_mfma_f32_32x32x16_bf16 v[98:113], v[164:167], v[122:125], v[98:113]
	ds_read_b128 v[164:167], v175 offset:13920
	v_cvt_f32_u32_e32 v152, v152
	v_add_f32_e32 v150, v187, v150
	v_add_f32_e32 v150, v188, v150
	v_add_f32_e32 v150, v191, v150
	v_add_f32_e32 v150, v189, v150
	v_add_f32_e32 v150, v190, v150
	s_waitcnt lgkmcnt(2)
	v_mfma_f32_32x32x16_bf16 v[82:97], v[156:159], v[122:125], v[82:97]
	v_add_f32_e32 v158, v151, v150
	s_waitcnt lgkmcnt(1)
	v_mfma_f32_32x32x16_bf16 v[98:113], v[160:163], v[126:129], v[98:113]
	v_sub_f32_e32 v160, v172, v152
	v_add_f32_e32 v161, -1.0, v160
	v_and_b32_e32 v150, 0x7fffffff, v160
	v_and_b32_e32 v151, 0x7fffffff, v161
	s_waitcnt lgkmcnt(0)
	v_mfma_f32_32x32x16_bf16 v[82:97], v[164:167], v[126:129], v[82:97]
	s_nop 15
	s_nop 7
	s_nop 5
	v_pk_fma_f32 v[150:151], v[142:143], v[150:151], v[98:99] neg_lo:[1,0,0] neg_hi:[1,0,0]
	v_pk_add_f32 v[98:99], v[160:161], s[8:9] op_sel_hi:[1,0]
	s_nop 0
	v_fma_f32 v83, -v143, |v99|, v83
	v_fma_f32 v82, -v142, |v98|, v82
	s_nop 0
	v_pk_add_f32 v[98:99], v[160:161], s[10:11] op_sel_hi:[0,1]
	v_fma_f32 v153, -v143, |v99|, v101
	v_fma_f32 v152, -v142, |v98|, v100
	v_pk_add_f32 v[98:99], v[98:99], s[8:9] op_sel_hi:[1,0]
	v_fma_f32 v99, -v143, |v99|, v85
	v_fma_f32 v98, -v142, |v98|, v84
	v_pk_add_f32 v[84:85], v[160:161], s[22:23] op_sel_hi:[0,1]
	v_fma_f32 v155, -v143, |v85|, v103
	v_fma_f32 v154, -v142, |v84|, v102
	v_pk_add_f32 v[84:85], v[84:85], s[8:9] op_sel_hi:[1,0]
	v_fma_f32 v101, -v143, |v85|, v87
	v_fma_f32 v100, -v142, |v84|, v86
	v_pk_add_f32 v[84:85], v[160:161], s[34:35] op_sel_hi:[0,1]
	v_fma_f32 v157, -v143, |v85|, v105
	v_fma_f32 v156, -v142, |v84|, v104
	v_pk_add_f32 v[84:85], v[84:85], s[8:9] op_sel_hi:[1,0]
	v_fma_f32 v103, -v143, |v85|, v89
	v_fma_f32 v102, -v142, |v84|, v88
	v_pk_add_f32 v[84:85], v[160:161], s[36:37] op_sel_hi:[0,1]
	v_fma_f32 v105, -v143, |v85|, v107
	v_fma_f32 v104, -v142, |v84|, v106
	v_pk_add_f32 v[86:87], v[160:161], s[38:39] op_sel_hi:[0,1]
	v_pk_add_f32 v[84:85], v[84:85], s[8:9] op_sel_hi:[1,0]
	v_fma_f32 v107, -v143, |v87|, v109
	v_fma_f32 v106, -v142, |v86|, v108
	v_fma_f32 v85, -v143, |v85|, v91
	v_fma_f32 v84, -v142, |v84|, v90
	v_pk_add_f32 v[86:87], v[86:87], s[8:9] op_sel_hi:[1,0]
	v_pk_add_f32 v[88:89], v[160:161], s[40:41] op_sel_hi:[0,1]
	v_fma_f32 v87, -v143, |v87|, v93
	v_fma_f32 v86, -v142, |v86|, v92
	v_fma_f32 v93, -v143, |v89|, v111
	v_fma_f32 v92, -v142, |v88|, v110
	v_pk_add_f32 v[88:89], v[88:89], s[8:9] op_sel_hi:[1,0]
	v_fma_f32 v89, -v143, |v89|, v95
	v_fma_f32 v88, -v142, |v88|, v94
	v_pk_add_f32 v[90:91], v[160:161], s[42:43] op_sel_hi:[0,1]
	v_fma_f32 v95, -v143, |v91|, v113
	v_fma_f32 v94, -v142, |v90|, v112
	v_pk_add_f32 v[90:91], v[90:91], s[8:9] op_sel_hi:[1,0]
	v_fma_f32 v91, -v143, |v91|, v97
	v_fma_f32 v90, -v142, |v90|, v96
	v_max3_f32 v96, v150, v151, v82
	v_max3_f32 v97, v152, v153, v83
	v_max3_f32 v96, v96, v98, v99
	v_max3_f32 v97, v97, v156, v157
	v_max3_f32 v96, v96, v154, v155
	v_max3_f32 v97, v97, v102, v103
	v_max3_f32 v96, v96, v100, v101
	v_max3_f32 v97, v97, v106, v107
	v_max3_f32 v96, v96, v104, v105
	v_max3_f32 v97, v97, v86, v87
	v_max3_f32 v96, v96, v84, v85
	v_max3_f32 v97, v97, v94, v95
	v_max3_f32 v96, v96, v92, v93
	v_max3_f32 v97, v97, v90, v91
	v_max3_f32 v96, v96, v88, v89
	v_max_f32_e32 v97, v97, v97
	v_max_f32_e32 v96, v96, v96
	v_max_f32_e32 v96, v96, v97
	v_cmp_lt_f32_e32 vcc, s52, v96
	s_cbranch_vccz .LBB0_575
; template <int DQK, int DV, bool BIAS> ...
;     ...
;         if (__any(mx > 8.f)) {
;             mx = fmaxf(mx, __shfl_xor(mx, 32));
;             const float dl = fmaxf(mx, 0.f); mhat += dl;
;             const float f = __builtin_amdgcn_exp2f(-dl);
; #pragma unroll
;             for (int r = 0; r < 16; ++r) { p0[r] -= dl; p1[r] -= dl; negm[r] = -mhat; }
;             l *= f;
; #pragma unroll
;             for (int d = 0; d < NDT; ++d)
; #pragma unroll
;                 for (int r = 0; r < 16; ++r) o[d][r] *= f;
;         }
	v_and_b32_e32 v67, 64, v170
	v_xor_b32_e32 v66, 32, v170
	v_add_u32_e32 v67, 64, v67
	v_cmp_lt_i32_e32 vcc, v66, v67
	s_nop 1
	v_cndmask_b32_e32 v66, v170, v66, vcc
	v_lshlrev_b32_e32 v66, 2, v66
	ds_bpermute_b32 v66, v66, v96
	s_waitcnt lgkmcnt(0)
	v_max3_f32 v67, v96, v66, 0
	v_exp_f32_e64 v68, -v67
	v_add_f32_e32 v176, v176, v67
	v_xor_b32_e32 v66, 0x80000000, v176
	v_sub_f32_e32 v82, v82, v67
	v_sub_f32_e32 v83, v83, v67
	v_sub_f32_e32 v98, v98, v67
	v_sub_f32_e32 v99, v99, v67
	v_sub_f32_e32 v100, v100, v67
	v_sub_f32_e32 v101, v101, v67
	v_sub_f32_e32 v102, v102, v67
	v_sub_f32_e32 v103, v103, v67
	v_sub_f32_e32 v84, v84, v67
	v_sub_f32_e32 v85, v85, v67
	v_sub_f32_e32 v86, v86, v67
	v_sub_f32_e32 v87, v87, v67
	v_sub_f32_e32 v88, v88, v67
	v_sub_f32_e32 v89, v89, v67
	v_sub_f32_e32 v90, v90, v67
	v_sub_f32_e32 v91, v91, v67
	v_pk_mul_f32 v[64:65], v[64:65], v[68:69] op_sel_hi:[1,0]
	v_pk_mul_f32 v[62:63], v[62:63], v[68:69] op_sel_hi:[1,0]
	v_pk_mul_f32 v[60:61], v[60:61], v[68:69] op_sel_hi:[1,0]
	v_pk_mul_f32 v[58:59], v[58:59], v[68:69] op_sel_hi:[1,0]
	v_pk_mul_f32 v[56:57], v[56:57], v[68:69] op_sel_hi:[1,0]
	v_pk_mul_f32 v[54:55], v[54:55], v[68:69] op_sel_hi:[1,0]
	v_pk_mul_f32 v[52:53], v[52:53], v[68:69] op_sel_hi:[1,0]
	v_pk_mul_f32 v[50:51], v[50:51], v[68:69] op_sel_hi:[1,0]
	v_pk_mul_f32 v[48:49], v[48:49], v[68:69] op_sel_hi:[1,0]
	v_pk_mul_f32 v[46:47], v[46:47], v[68:69] op_sel_hi:[1,0]
	v_pk_mul_f32 v[44:45], v[44:45], v[68:69] op_sel_hi:[1,0]
	v_pk_mul_f32 v[42:43], v[42:43], v[68:69] op_sel_hi:[1,0]
	v_pk_mul_f32 v[40:41], v[40:41], v[68:69] op_sel_hi:[1,0]
	v_pk_mul_f32 v[38:39], v[38:39], v[68:69] op_sel_hi:[1,0]
	v_pk_mul_f32 v[36:37], v[36:37], v[68:69] op_sel_hi:[1,0]
	v_pk_mul_f32 v[34:35], v[34:35], v[68:69] op_sel_hi:[1,0]
	v_pk_mul_f32 v[32:33], v[32:33], v[68:69] op_sel_hi:[1,0]
	v_pk_mul_f32 v[30:31], v[30:31], v[68:69] op_sel_hi:[1,0]
	v_pk_mul_f32 v[28:29], v[28:29], v[68:69] op_sel_hi:[1,0]
	v_pk_mul_f32 v[26:27], v[26:27], v[68:69] op_sel_hi:[1,0]
	v_pk_mul_f32 v[24:25], v[24:25], v[68:69] op_sel_hi:[1,0]
	v_pk_mul_f32 v[22:23], v[22:23], v[68:69] op_sel_hi:[1,0]
	v_pk_mul_f32 v[20:21], v[20:21], v[68:69] op_sel_hi:[1,0]
	v_pk_mul_f32 v[18:19], v[18:19], v[68:69] op_sel_hi:[1,0]
	v_pk_mul_f32 v[16:17], v[16:17], v[68:69] op_sel_hi:[1,0]
	v_pk_mul_f32 v[14:15], v[14:15], v[68:69] op_sel_hi:[1,0]
	v_pk_mul_f32 v[12:13], v[12:13], v[68:69] op_sel_hi:[1,0]
	v_pk_mul_f32 v[10:11], v[10:11], v[68:69] op_sel_hi:[1,0]
	v_pk_mul_f32 v[8:9], v[8:9], v[68:69] op_sel_hi:[1,0]
	v_pk_mul_f32 v[6:7], v[6:7], v[68:69] op_sel_hi:[1,0]
	v_pk_mul_f32 v[4:5], v[4:5], v[68:69] op_sel_hi:[1,0]
	v_pk_mul_f32 v[2:3], v[2:3], v[68:69] op_sel_hi:[1,0]
	v_sub_f32_e32 v150, v150, v67
	v_sub_f32_e32 v151, v151, v67
	v_sub_f32_e32 v152, v152, v67
	v_sub_f32_e32 v153, v153, v67
	v_sub_f32_e32 v154, v154, v67
	v_sub_f32_e32 v155, v155, v67
	v_sub_f32_e32 v156, v156, v67
	v_sub_f32_e32 v157, v157, v67
	v_sub_f32_e32 v104, v104, v67
	v_sub_f32_e32 v105, v105, v67
	v_sub_f32_e32 v106, v106, v67
	v_sub_f32_e32 v107, v107, v67
	v_sub_f32_e32 v92, v92, v67
	v_sub_f32_e32 v93, v93, v67
	v_sub_f32_e32 v94, v94, v67
	v_sub_f32_e32 v95, v95, v67
	v_mul_f32_e32 v158, v158, v68
	v_mov_b32_e32 v67, v66
	v_mov_b32_e32 v68, v66
	v_mov_b32_e32 v69, v66
	v_mov_b32_e32 v70, v66
	v_mov_b32_e32 v71, v66
	v_mov_b32_e32 v72, v66
	v_mov_b32_e32 v73, v66
	v_mov_b32_e32 v74, v66
	v_mov_b32_e32 v75, v66
	v_mov_b32_e32 v76, v66
	v_mov_b32_e32 v77, v66
	v_mov_b32_e32 v78, v66
	v_mov_b32_e32 v79, v66
	v_mov_b32_e32 v80, v66
	v_mov_b32_e32 v81, v66
	s_branch .LBB0_575

; #define LAS __attribute__((address_space(3)))
; __device__ __forceinline__ float max3f(float a, float b, float c) { float r; asm("v_max3_f32 %0, %1, %2, %3" : "=v"(r) : "v"(a), "v"(b), "v"(c)); return r; }
; template <int DQK, int DV, bool BIAS> ...
;     ...
;         const LAS unsigned char* kb = lds + buf * KBUF + r32 * KP + hi * 16;
; #pragma unroll
;         for (int ks = 0; ks < NKS; ++ks) {
;             const bf16x8 k0 = *(const LAS bf16x8*)(kb + ks * 32), k1 = *(const LAS bf16x8*)(kb + 32 * KP + ks * 32);
;             if (ks == 0) { p0 = __builtin_amdgcn_mfma_f32_32x32x16_bf16(k0, qf[0], negm, 0, 0, 0); p1 = __builtin_amdgcn_mfma_f32_32x32x16_bf16(k1, qf[0], negm, 0, 0, 0); }
;             else { p0 = __builtin_amdgcn_mfma_f32_32x32x16_bf16(k0, qf[ks], p0, 0, 0, 0); p1 = __builtin_amdgcn_mfma_f32_32x32x16_bf16(k1, qf[ks], p1, 0, 0, 0); }
;         }
;         if (BIAS) {
;             asm volatile("s_nop 15\n\ts_nop 7" : "+v"(p0), "+v"(p1));
;             const float d0 = qp - (float)(t * 64 + 4 * hi);
; #pragma unroll
;             for (int r = 0; r < 16; ++r) { const float dk = d0 - (float)((r & 3) + 8 * (r >> 2)); p0[r] = p0[r] - sl2 * fabsf(dk); p1[r] = p1[r] - sl2 * fabsf(dk - 32.f); }
;         } else {
;             asm volatile("s_nop 15\n\ts_nop 7" : "+v"(p0), "+v"(p1));
;         }
;         float mxa = max3f(p0[0], p0[1], p1[0]), mxb = max3f(p0[2], p0[3], p1[1]); mxa = max3f(mxa, p1[2], p1[3]);
; #pragma unroll
;         for (int r = 4; r < 16; r += 4) { mxa = max3f(mxa, p0[r], p0[r + 1]); mxb = max3f(mxb, p0[r + 2], p0[r + 3]); mxa = max3f(mxa, p1[r], p1[r + 1]); mxb = max3f(mxb, p1[r + 2], p1[r + 3]); }
;         float mx = fmaxf(mxa, mxb);
;         if (__any(mx > 8.f)) {
.LBB0_590:
	ds_read_b128 v[82:85], v179
	ds_read_b128 v[152:155], v179 offset:32
	ds_read_b128 v[156:159], v179 offset:4608
	ds_read_b128 v[160:163], v179 offset:4640
	v_cvt_f32_u32_e32 v150, v177
	s_waitcnt lgkmcnt(3)
	v_mfma_f32_32x32x16_bf16 v[98:113], v[82:85], v[114:117], v[66:81]
	v_sub_f32_e32 v182, v176, v150
	v_add_f32_e32 v183, -1.0, v182
	s_waitcnt lgkmcnt(1)
	v_mfma_f32_32x32x16_bf16 v[82:97], v[156:159], v[114:117], v[66:81]
	v_mfma_f32_32x32x16_bf16 v[98:113], v[152:155], v[118:121], v[98:113]
	ds_read_b128 v[152:155], v179 offset:64
	ds_read_b128 v[156:159], v179 offset:96
	s_waitcnt lgkmcnt(2)
	v_mfma_f32_32x32x16_bf16 v[82:97], v[160:163], v[118:121], v[82:97]
	s_waitcnt lgkmcnt(1)
	v_mfma_f32_32x32x16_bf16 v[98:113], v[152:155], v[122:125], v[98:113]
	ds_read_b128 v[152:155], v179 offset:4672
	ds_read_b128 v[160:163], v179 offset:4704
	s_waitcnt lgkmcnt(1)
	v_mfma_f32_32x32x16_bf16 v[82:97], v[152:155], v[122:125], v[82:97]
	v_and_b32_e32 v152, 0x7fffffff, v182
	v_and_b32_e32 v153, 0x7fffffff, v183
	v_mfma_f32_32x32x16_bf16 v[98:113], v[156:159], v[126:129], v[98:113]
	s_waitcnt lgkmcnt(0)
	v_mfma_f32_32x32x16_bf16 v[82:97], v[160:163], v[126:129], v[82:97]
	s_nop 15
	s_nop 7
	s_nop 9
	v_pk_fma_f32 v[156:157], v[142:143], v[152:153], v[98:99] neg_lo:[1,0,0] neg_hi:[1,0,0]
	v_pk_add_f32 v[98:99], v[182:183], s[6:7] op_sel_hi:[1,0]
	s_nop 0
	v_fma_f32 v99, -v143, |v99|, v83
	v_fma_f32 v98, -v142, |v98|, v82
	v_pk_add_f32 v[82:83], v[182:183], s[8:9] op_sel_hi:[0,1]
	v_fma_f32 v161, -v143, |v83|, v101
	v_fma_f32 v160, -v142, |v82|, v100
	v_pk_add_f32 v[82:83], v[82:83], s[6:7] op_sel_hi:[1,0]
	v_fma_f32 v153, -v143, |v83|, v85
	v_fma_f32 v152, -v142, |v82|, v84
	v_pk_add_f32 v[82:83], v[182:183], s[10:11] op_sel_hi:[0,1]
	v_fma_f32 v165, -v143, |v83|, v103
	v_fma_f32 v164, -v142, |v82|, v102
	v_pk_add_f32 v[82:83], v[82:83], s[6:7] op_sel_hi:[1,0]
	v_fma_f32 v103, -v143, |v83|, v87
	v_fma_f32 v102, -v142, |v82|, v86
	v_pk_add_f32 v[82:83], v[182:183], s[22:23] op_sel_hi:[0,1]
	v_fma_f32 v167, -v143, |v83|, v105
	v_fma_f32 v166, -v142, |v82|, v104
	v_pk_add_f32 v[82:83], v[82:83], s[6:7] op_sel_hi:[1,0]
	v_fma_f32 v155, -v143, |v83|, v89
	v_fma_f32 v154, -v142, |v82|, v88
	v_pk_add_f32 v[82:83], v[182:183], s[34:35] op_sel_hi:[0,1]
	v_fma_f32 v159, -v143, |v83|, v107
	v_fma_f32 v158, -v142, |v82|, v106
	v_pk_add_f32 v[82:83], v[82:83], s[6:7] op_sel_hi:[1,0]
	v_fma_f32 v101, -v143, |v83|, v91
	v_fma_f32 v100, -v142, |v82|, v90
	v_pk_add_f32 v[82:83], v[182:183], s[36:37] op_sel_hi:[0,1]
	v_fma_f32 v163, -v143, |v83|, v109
	v_fma_f32 v162, -v142, |v82|, v108
	v_pk_add_f32 v[82:83], v[82:83], s[6:7] op_sel_hi:[1,0]
	v_fma_f32 v105, -v143, |v83|, v93
	v_fma_f32 v104, -v142, |v82|, v92
	v_pk_add_f32 v[82:83], v[182:183], s[38:39] op_sel_hi:[0,1]
	v_fma_f32 v111, -v143, |v83|, v111
	v_fma_f32 v110, -v142, |v82|, v110
	v_pk_add_f32 v[82:83], v[82:83], s[6:7] op_sel_hi:[1,0]
	v_fma_f32 v107, -v143, |v83|, v95
	v_fma_f32 v106, -v142, |v82|, v94
	v_pk_add_f32 v[82:83], v[182:183], s[40:41] op_sel_hi:[0,1]
	v_fma_f32 v113, -v143, |v83|, v113
	v_fma_f32 v112, -v142, |v82|, v112
	v_pk_add_f32 v[82:83], v[82:83], s[6:7] op_sel_hi:[1,0]
	v_fma_f32 v109, -v143, |v83|, v97
	v_fma_f32 v108, -v142, |v82|, v96
	v_max3_f32 v82, v156, v157, v98
	v_max3_f32 v83, v160, v161, v99
	v_max3_f32 v82, v82, v152, v153
	v_max3_f32 v83, v83, v166, v167
	v_max3_f32 v82, v82, v164, v165
	v_max3_f32 v83, v83, v154, v155
	v_max3_f32 v82, v82, v102, v103
	v_max3_f32 v83, v83, v162, v163
	v_max3_f32 v82, v82, v158, v159
	v_max3_f32 v83, v83, v104, v105
	v_max3_f32 v82, v82, v100, v101
	v_max3_f32 v83, v83, v112, v113
	v_max3_f32 v82, v82, v110, v111
	v_max3_f32 v83, v83, v108, v109
	v_max3_f32 v82, v82, v106, v107
	v_max_f32_e32 v83, v83, v83
	v_max_f32_e32 v82, v82, v82
	v_max_f32_e32 v82, v82, v83
	v_cmp_lt_f32_e32 vcc, s44, v82
	s_cbranch_vccz .LBB0_592
; template <int DQK, int DV, bool BIAS> ...
;     ...
;         if (__any(mx > 8.f)) {
;             mx = fmaxf(mx, __shfl_xor(mx, 32));
;             const float dl = fmaxf(mx, 0.f); mhat += dl;
;             const float f = __builtin_amdgcn_exp2f(-dl);
; #pragma unroll
;             for (int r = 0; r < 16; ++r) { p0[r] -= dl; p1[r] -= dl; negm[r] = -mhat; }
;             l *= f;
; #pragma unroll
;             for (int d = 0; d < NDT; ++d)
; #pragma unroll
;                 for (int r = 0; r < 16; ++r) o[d][r] *= f;
;         }
	ds_bpermute_b32 v66, v168, v82
	s_waitcnt lgkmcnt(0)
	v_max3_f32 v67, v82, v66, 0
	v_exp_f32_e64 v66, -v67
	v_add_f32_e32 v180, v180, v67
	v_xor_b32_e32 v82, 0x80000000, v180
	v_sub_f32_e32 v98, v98, v67
	v_sub_f32_e32 v99, v99, v67
	v_sub_f32_e32 v152, v152, v67
	v_sub_f32_e32 v153, v153, v67
	v_sub_f32_e32 v102, v102, v67
	v_sub_f32_e32 v103, v103, v67
	v_sub_f32_e32 v154, v154, v67
	v_sub_f32_e32 v155, v155, v67
	v_sub_f32_e32 v100, v100, v67
	v_sub_f32_e32 v101, v101, v67
	v_sub_f32_e32 v104, v104, v67
	v_sub_f32_e32 v105, v105, v67
	v_sub_f32_e32 v106, v106, v67
	v_sub_f32_e32 v107, v107, v67
	v_sub_f32_e32 v108, v108, v67
	v_sub_f32_e32 v109, v109, v67
	v_pk_mul_f32 v[16:17], v[16:17], v[66:67] op_sel_hi:[1,0]
	v_pk_mul_f32 v[14:15], v[14:15], v[66:67] op_sel_hi:[1,0]
	v_pk_mul_f32 v[12:13], v[12:13], v[66:67] op_sel_hi:[1,0]
	v_pk_mul_f32 v[10:11], v[10:11], v[66:67] op_sel_hi:[1,0]
	v_pk_mul_f32 v[8:9], v[8:9], v[66:67] op_sel_hi:[1,0]
	v_pk_mul_f32 v[6:7], v[6:7], v[66:67] op_sel_hi:[1,0]
	v_pk_mul_f32 v[4:5], v[4:5], v[66:67] op_sel_hi:[1,0]
	v_pk_mul_f32 v[2:3], v[2:3], v[66:67] op_sel_hi:[1,0]
	v_pk_mul_f32 v[32:33], v[32:33], v[66:67] op_sel_hi:[1,0]
	v_pk_mul_f32 v[30:31], v[30:31], v[66:67] op_sel_hi:[1,0]
	v_pk_mul_f32 v[28:29], v[28:29], v[66:67] op_sel_hi:[1,0]
	v_pk_mul_f32 v[26:27], v[26:27], v[66:67] op_sel_hi:[1,0]
	v_pk_mul_f32 v[24:25], v[24:25], v[66:67] op_sel_hi:[1,0]
	v_pk_mul_f32 v[22:23], v[22:23], v[66:67] op_sel_hi:[1,0]
	v_pk_mul_f32 v[20:21], v[20:21], v[66:67] op_sel_hi:[1,0]
	v_pk_mul_f32 v[18:19], v[18:19], v[66:67] op_sel_hi:[1,0]
	v_pk_mul_f32 v[48:49], v[48:49], v[66:67] op_sel_hi:[1,0]
	v_pk_mul_f32 v[46:47], v[46:47], v[66:67] op_sel_hi:[1,0]
	v_pk_mul_f32 v[44:45], v[44:45], v[66:67] op_sel_hi:[1,0]
	v_pk_mul_f32 v[42:43], v[42:43], v[66:67] op_sel_hi:[1,0]
	v_pk_mul_f32 v[40:41], v[40:41], v[66:67] op_sel_hi:[1,0]
	v_pk_mul_f32 v[38:39], v[38:39], v[66:67] op_sel_hi:[1,0]
	v_pk_mul_f32 v[36:37], v[36:37], v[66:67] op_sel_hi:[1,0]
	v_pk_mul_f32 v[34:35], v[34:35], v[66:67] op_sel_hi:[1,0]
	v_pk_mul_f32 v[64:65], v[64:65], v[66:67] op_sel_hi:[1,0]
	v_pk_mul_f32 v[62:63], v[62:63], v[66:67] op_sel_hi:[1,0]
	v_pk_mul_f32 v[60:61], v[60:61], v[66:67] op_sel_hi:[1,0]
	v_pk_mul_f32 v[58:59], v[58:59], v[66:67] op_sel_hi:[1,0]
	v_pk_mul_f32 v[56:57], v[56:57], v[66:67] op_sel_hi:[1,0]
	v_pk_mul_f32 v[54:55], v[54:55], v[66:67] op_sel_hi:[1,0]
	v_pk_mul_f32 v[52:53], v[52:53], v[66:67] op_sel_hi:[1,0]
	v_pk_mul_f32 v[50:51], v[50:51], v[66:67] op_sel_hi:[1,0]
	v_sub_f32_e32 v156, v156, v67
	v_sub_f32_e32 v157, v157, v67
	v_sub_f32_e32 v160, v160, v67
	v_sub_f32_e32 v161, v161, v67
	v_sub_f32_e32 v164, v164, v67
	v_sub_f32_e32 v165, v165, v67
	v_sub_f32_e32 v166, v166, v67
	v_sub_f32_e32 v167, v167, v67
	v_sub_f32_e32 v158, v158, v67
	v_sub_f32_e32 v159, v159, v67
	v_sub_f32_e32 v162, v162, v67
	v_sub_f32_e32 v163, v163, v67
	v_sub_f32_e32 v110, v110, v67
	v_sub_f32_e32 v111, v111, v67
	v_sub_f32_e32 v112, v112, v67
	v_sub_f32_e32 v113, v113, v67
	v_mul_f32_e32 v151, v151, v66
	v_mov_b32_e32 v83, v82
	v_mov_b32_e32 v84, v82
	v_mov_b32_e32 v85, v82
	v_mov_b32_e32 v86, v82
	v_mov_b32_e32 v87, v82
	v_mov_b32_e32 v88, v82
	v_mov_b32_e32 v89, v82
	v_mov_b32_e32 v90, v82
	v_mov_b32_e32 v91, v82
	v_mov_b32_e32 v92, v82
	v_mov_b32_e32 v93, v82
	v_mov_b32_e32 v94, v82
	v_mov_b32_e32 v95, v82
	v_mov_b32_e32 v96, v82
	v_mov_b32_e32 v97, v82
	v_mov_b32_e32 v66, v82
	v_mov_b32_e32 v67, v82
	v_mov_b32_e32 v68, v82
	v_mov_b32_e32 v69, v82
	v_mov_b32_e32 v70, v82
	v_mov_b32_e32 v71, v82
	v_mov_b32_e32 v72, v82
	v_mov_b32_e32 v73, v82
	v_mov_b32_e32 v74, v82
	v_mov_b32_e32 v75, v82
	v_mov_b32_e32 v76, v82
	v_mov_b32_e32 v77, v82
	v_mov_b32_e32 v78, v82
	v_mov_b32_e32 v79, v82
	v_mov_b32_e32 v80, v82
	v_mov_b32_e32 v81, v82
	s_branch .LBB0_593

; template <int DQK, int DV, bool BIAS> ...
;     ...
;         const LAS unsigned char* kb = lds + buf * KBUF + r32 * KP + hi * 16;
; #pragma unroll
;         for (int ks = 0; ks < NKS; ++ks) {
;             const bf16x8 k0 = *(const LAS bf16x8*)(kb + ks * 32), k1 = *(const LAS bf16x8*)(kb + 32 * KP + ks * 32);
;             if (ks == 0) { p0 = __builtin_amdgcn_mfma_f32_32x32x16_bf16(k0, qf[0], negm, 0, 0, 0); p1 = __builtin_amdgcn_mfma_f32_32x32x16_bf16(k1, qf[0], negm, 0, 0, 0); }
;             else { p0 = __builtin_amdgcn_mfma_f32_32x32x16_bf16(k0, qf[ks], p0, 0, 0, 0); p1 = __builtin_amdgcn_mfma_f32_32x32x16_bf16(k1, qf[ks], p1, 0, 0, 0); }
;         }
;         if (BIAS) {
;             asm volatile("s_nop 15\n\ts_nop 7" : "+v"(p0), "+v"(p1));
;             const float d0 = qp - (float)(t * 64 + 4 * hi);
; #pragma unroll
;             for (int r = 0; r < 16; ++r) { const float dk = d0 - (float)((r & 3) + 8 * (r >> 2)); p0[r] = p0[r] - sl2 * fabsf(dk); p1[r] = p1[r] - sl2 * fabsf(dk - 32.f); }
;         } else {
;             asm volatile("s_nop 15\n\ts_nop 7" : "+v"(p0), "+v"(p1));
;         }
;         float mxa = max3f(p0[0], p0[1], p1[0]), mxb = max3f(p0[2], p0[3], p1[1]); mxa = max3f(mxa, p1[2], p1[3]);
; #pragma unroll
;         for (int r = 4; r < 16; r += 4) { mxa = max3f(mxa, p0[r], p0[r + 1]); mxb = max3f(mxb, p0[r + 2], p0[r + 3]); mxa = max3f(mxa, p1[r], p1[r + 1]); mxb = max3f(mxb, p1[r + 2], p1[r + 3]); }
;         float mx = fmaxf(mxa, mxb);
;         if (__any(mx > 8.f)) {
;     ...
;                 for (int j = 0; j < 8; ++j) { e[j] = __builtin_amdgcn_exp2f(hs < 2 ? p0[8 * (hs & 1) + j] : p1[8 * (hs & 1) + j]); ls += e[j]; }
;                 pw[hs].x = cvtpk(e[0], e[1]); pw[hs].y = cvtpk(e[2], e[3]); pw[hs].z = cvtpk(e[4], e[5]); pw[hs].w = cvtpk(e[6], e[7]);
;                 const bf16x8 pbv = __builtin_bit_cast(bf16x8, pw[hs]);
; #pragma unroll
;                 for (int d = 0; d < NDT; ++d) { const LAS unsigned char* vp = vbase + d * 4096 + hs * 1024;
;                     const v4i16_t a0 = __builtin_amdgcn_ds_read_tr16_b64_v4i16((LAS v4i16_t*)vp), a1 = __builtin_amdgcn_ds_read_tr16_b64_v4i16((LAS v4i16_t*)(vp + 512));
;                     const bf16x8 av = {a0[0], a0[1], a0[2], a0[3], a1[0], a1[1], a1[2], a1[3]};
;                     o[d] = __builtin_amdgcn_mfma_f32_32x32x16_bf16(av, pbv, o[d], 0, 0, 0); }
.LBB0_596:
	ds_read_b128 v[196:199], v179 offset:9216
	ds_read_b128 v[200:203], v179 offset:9248
	v_add_f32_e32 v156, 0, v156
	v_add_f32_e32 v156, v157, v156
	v_add_f32_e32 v156, v160, v156
	s_waitcnt lgkmcnt(1)
	v_mfma_f32_32x32x16_bf16 v[98:113], v[196:199], v[114:117], v[82:97]
	ds_read_b128 v[196:199], v179 offset:13824
	ds_read_b128 v[204:207], v179 offset:13856
	v_add_f32_e32 v156, v161, v156
	v_add_f32_e32 v156, v164, v156
	v_add_f32_e32 v150, v150, v156
	v_add_f32_e32 v150, v165, v150
	v_add_f32_e32 v150, v166, v150
	v_add_f32_e32 v150, v167, v150
	s_waitcnt lgkmcnt(1)
	v_mfma_f32_32x32x16_bf16 v[82:97], v[196:199], v[114:117], v[82:97]
	v_add_f32_e32 v150, v181, v150
	v_add_f32_e32 v150, v182, v150
	v_add_f32_e32 v150, v158, v150
	v_add_f32_e32 v150, v159, v150
	ds_read_b128 v[164:167], v179 offset:9280
	v_add_f32_e32 v150, v162, v150
	v_add_f32_e32 v150, v163, v150
	v_mfma_f32_32x32x16_bf16 v[98:113], v[200:203], v[118:121], v[98:113]
	v_add_f32_e32 v150, v183, v150
	v_add_f32_e32 v150, v184, v150
	v_add_f32_e32 v150, v185, v150
	v_add_f32_e32 v150, v152, v150
	ds_read_b128 v[156:159], v179 offset:13888
	ds_read_b128 v[160:163], v179 offset:9312
	v_add_f32_e32 v150, v153, v150
	v_add_f32_e32 v150, v186, v150
	s_waitcnt lgkmcnt(3)
	v_mfma_f32_32x32x16_bf16 v[82:97], v[204:207], v[118:121], v[82:97]
	v_add_f32_e32 v150, v187, v150
	v_add_f32_e32 v150, v154, v150
	v_add_f32_e32 v150, v155, v150
	v_add_f32_e32 v150, v188, v150
	v_add_f32_e32 v150, v189, v150
	v_add_u32_e32 v152, 64, v177
	v_add_f32_e32 v150, v190, v150
	s_waitcnt lgkmcnt(2)
	v_mfma_f32_32x32x16_bf16 v[98:113], v[164:167], v[122:125], v[98:113]
	ds_read_b128 v[164:167], v179 offset:13920
	v_cvt_f32_u32_e32 v152, v152
	v_add_f32_e32 v150, v191, v150
	v_add_f32_e32 v150, v192, v150
	v_add_f32_e32 v150, v195, v150
	v_add_f32_e32 v150, v193, v150
	v_add_f32_e32 v150, v194, v150
	s_waitcnt lgkmcnt(2)
	v_mfma_f32_32x32x16_bf16 v[82:97], v[156:159], v[122:125], v[82:97]
	v_add_f32_e32 v158, v151, v150
	s_waitcnt lgkmcnt(1)
	v_mfma_f32_32x32x16_bf16 v[98:113], v[160:163], v[126:129], v[98:113]
	v_sub_f32_e32 v160, v176, v152
	v_add_f32_e32 v161, -1.0, v160
	v_and_b32_e32 v150, 0x7fffffff, v160
	v_and_b32_e32 v151, 0x7fffffff, v161
	s_waitcnt lgkmcnt(0)
	v_mfma_f32_32x32x16_bf16 v[82:97], v[164:167], v[126:129], v[82:97]
	s_nop 15
	s_nop 7
	s_nop 5
	v_pk_fma_f32 v[150:151], v[142:143], v[150:151], v[98:99] neg_lo:[1,0,0] neg_hi:[1,0,0]
	v_pk_add_f32 v[98:99], v[160:161], s[6:7] op_sel_hi:[1,0]
	s_nop 0
	v_fma_f32 v83, -v143, |v99|, v83
	v_fma_f32 v82, -v142, |v98|, v82
	s_nop 0
	v_pk_add_f32 v[98:99], v[160:161], s[8:9] op_sel_hi:[0,1]
	v_fma_f32 v153, -v143, |v99|, v101
	v_fma_f32 v152, -v142, |v98|, v100
	v_pk_add_f32 v[98:99], v[98:99], s[6:7] op_sel_hi:[1,0]
	v_fma_f32 v99, -v143, |v99|, v85
	v_fma_f32 v98, -v142, |v98|, v84
	v_pk_add_f32 v[84:85], v[160:161], s[10:11] op_sel_hi:[0,1]
	v_fma_f32 v155, -v143, |v85|, v103
	v_fma_f32 v154, -v142, |v84|, v102
	v_pk_add_f32 v[84:85], v[84:85], s[6:7] op_sel_hi:[1,0]
	v_fma_f32 v101, -v143, |v85|, v87
	v_fma_f32 v100, -v142, |v84|, v86
	v_pk_add_f32 v[84:85], v[160:161], s[22:23] op_sel_hi:[0,1]
	v_fma_f32 v157, -v143, |v85|, v105
	v_fma_f32 v156, -v142, |v84|, v104
	v_pk_add_f32 v[84:85], v[84:85], s[6:7] op_sel_hi:[1,0]
	v_fma_f32 v103, -v143, |v85|, v89
	v_fma_f32 v102, -v142, |v84|, v88
	v_pk_add_f32 v[84:85], v[160:161], s[34:35] op_sel_hi:[0,1]
	v_fma_f32 v105, -v143, |v85|, v107
	v_fma_f32 v104, -v142, |v84|, v106
	v_pk_add_f32 v[86:87], v[160:161], s[36:37] op_sel_hi:[0,1]
	v_pk_add_f32 v[84:85], v[84:85], s[6:7] op_sel_hi:[1,0]
	v_fma_f32 v107, -v143, |v87|, v109
	v_fma_f32 v106, -v142, |v86|, v108
	v_fma_f32 v85, -v143, |v85|, v91
	v_fma_f32 v84, -v142, |v84|, v90
	v_pk_add_f32 v[86:87], v[86:87], s[6:7] op_sel_hi:[1,0]
	v_pk_add_f32 v[88:89], v[160:161], s[38:39] op_sel_hi:[0,1]
	v_fma_f32 v87, -v143, |v87|, v93
	v_fma_f32 v86, -v142, |v86|, v92
	v_fma_f32 v93, -v143, |v89|, v111
	v_fma_f32 v92, -v142, |v88|, v110
	v_pk_add_f32 v[88:89], v[88:89], s[6:7] op_sel_hi:[1,0]
	v_fma_f32 v89, -v143, |v89|, v95
	v_fma_f32 v88, -v142, |v88|, v94
	v_pk_add_f32 v[90:91], v[160:161], s[40:41] op_sel_hi:[0,1]
	v_fma_f32 v95, -v143, |v91|, v113
	v_fma_f32 v94, -v142, |v90|, v112
	v_pk_add_f32 v[90:91], v[90:91], s[6:7] op_sel_hi:[1,0]
	v_fma_f32 v91, -v143, |v91|, v97
	v_fma_f32 v90, -v142, |v90|, v96
	v_max3_f32 v96, v150, v151, v82
	v_max3_f32 v97, v152, v153, v83
	v_max3_f32 v96, v96, v98, v99
	v_max3_f32 v97, v97, v156, v157
	v_max3_f32 v96, v96, v154, v155
	v_max3_f32 v97, v97, v102, v103
	v_max3_f32 v96, v96, v100, v101
	v_max3_f32 v97, v97, v106, v107
	v_max3_f32 v96, v96, v104, v105
	v_max3_f32 v97, v97, v86, v87
	v_max3_f32 v96, v96, v84, v85
	v_max3_f32 v97, v97, v94, v95
	v_max3_f32 v96, v96, v92, v93
	v_max3_f32 v97, v97, v90, v91
	v_max3_f32 v96, v96, v88, v89
	v_max_f32_e32 v97, v97, v97
	v_max_f32_e32 v96, v96, v96
	v_max_f32_e32 v96, v96, v97
	v_cmp_lt_f32_e32 vcc, s44, v96
	s_cbranch_vccz .LBB0_587
; template <int DQK, int DV, bool BIAS> ...
;     ...
;         if (__any(mx > 8.f)) {
;             mx = fmaxf(mx, __shfl_xor(mx, 32));
;             const float dl = fmaxf(mx, 0.f); mhat += dl;
;             const float f = __builtin_amdgcn_exp2f(-dl);
; #pragma unroll
;             for (int r = 0; r < 16; ++r) { p0[r] -= dl; p1[r] -= dl; negm[r] = -mhat; }
;             l *= f;
; #pragma unroll
;             for (int d = 0; d < NDT; ++d)
; #pragma unroll
;                 for (int r = 0; r < 16; ++r) o[d][r] *= f;
;         }
	ds_bpermute_b32 v66, v168, v96
	s_waitcnt lgkmcnt(0)
	v_max3_f32 v67, v96, v66, 0
	v_exp_f32_e64 v68, -v67
	v_add_f32_e32 v180, v180, v67
	v_xor_b32_e32 v66, 0x80000000, v180
	v_sub_f32_e32 v82, v82, v67
	v_sub_f32_e32 v83, v83, v67
	v_sub_f32_e32 v98, v98, v67
	v_sub_f32_e32 v99, v99, v67
	v_sub_f32_e32 v100, v100, v67
	v_sub_f32_e32 v101, v101, v67
	v_sub_f32_e32 v102, v102, v67
	v_sub_f32_e32 v103, v103, v67
	v_sub_f32_e32 v84, v84, v67
	v_sub_f32_e32 v85, v85, v67
	v_sub_f32_e32 v86, v86, v67
	v_sub_f32_e32 v87, v87, v67
	v_sub_f32_e32 v88, v88, v67
	v_sub_f32_e32 v89, v89, v67
	v_sub_f32_e32 v90, v90, v67
	v_sub_f32_e32 v91, v91, v67
	v_pk_mul_f32 v[16:17], v[16:17], v[68:69] op_sel_hi:[1,0]
	v_pk_mul_f32 v[14:15], v[14:15], v[68:69] op_sel_hi:[1,0]
	v_pk_mul_f32 v[12:13], v[12:13], v[68:69] op_sel_hi:[1,0]
	v_pk_mul_f32 v[10:11], v[10:11], v[68:69] op_sel_hi:[1,0]
	v_pk_mul_f32 v[8:9], v[8:9], v[68:69] op_sel_hi:[1,0]
	v_pk_mul_f32 v[6:7], v[6:7], v[68:69] op_sel_hi:[1,0]
	v_pk_mul_f32 v[4:5], v[4:5], v[68:69] op_sel_hi:[1,0]
	v_pk_mul_f32 v[2:3], v[2:3], v[68:69] op_sel_hi:[1,0]
	v_pk_mul_f32 v[32:33], v[32:33], v[68:69] op_sel_hi:[1,0]
	v_pk_mul_f32 v[30:31], v[30:31], v[68:69] op_sel_hi:[1,0]
	v_pk_mul_f32 v[28:29], v[28:29], v[68:69] op_sel_hi:[1,0]
	v_pk_mul_f32 v[26:27], v[26:27], v[68:69] op_sel_hi:[1,0]
	v_pk_mul_f32 v[24:25], v[24:25], v[68:69] op_sel_hi:[1,0]
	v_pk_mul_f32 v[22:23], v[22:23], v[68:69] op_sel_hi:[1,0]
	v_pk_mul_f32 v[20:21], v[20:21], v[68:69] op_sel_hi:[1,0]
	v_pk_mul_f32 v[18:19], v[18:19], v[68:69] op_sel_hi:[1,0]
	v_pk_mul_f32 v[48:49], v[48:49], v[68:69] op_sel_hi:[1,0]
	v_pk_mul_f32 v[46:47], v[46:47], v[68:69] op_sel_hi:[1,0]
	v_pk_mul_f32 v[44:45], v[44:45], v[68:69] op_sel_hi:[1,0]
	v_pk_mul_f32 v[42:43], v[42:43], v[68:69] op_sel_hi:[1,0]
	v_pk_mul_f32 v[40:41], v[40:41], v[68:69] op_sel_hi:[1,0]
	v_pk_mul_f32 v[38:39], v[38:39], v[68:69] op_sel_hi:[1,0]
	v_pk_mul_f32 v[36:37], v[36:37], v[68:69] op_sel_hi:[1,0]
	v_pk_mul_f32 v[34:35], v[34:35], v[68:69] op_sel_hi:[1,0]
	v_pk_mul_f32 v[64:65], v[64:65], v[68:69] op_sel_hi:[1,0]
	v_pk_mul_f32 v[62:63], v[62:63], v[68:69] op_sel_hi:[1,0]
	v_pk_mul_f32 v[60:61], v[60:61], v[68:69] op_sel_hi:[1,0]
	v_pk_mul_f32 v[58:59], v[58:59], v[68:69] op_sel_hi:[1,0]
	v_pk_mul_f32 v[56:57], v[56:57], v[68:69] op_sel_hi:[1,0]
	v_pk_mul_f32 v[54:55], v[54:55], v[68:69] op_sel_hi:[1,0]
	v_pk_mul_f32 v[52:53], v[52:53], v[68:69] op_sel_hi:[1,0]
	v_pk_mul_f32 v[50:51], v[50:51], v[68:69] op_sel_hi:[1,0]
	v_sub_f32_e32 v150, v150, v67
	v_sub_f32_e32 v151, v151, v67
	v_sub_f32_e32 v152, v152, v67
	v_sub_f32_e32 v153, v153, v67
	v_sub_f32_e32 v154, v154, v67
	v_sub_f32_e32 v155, v155, v67
	v_sub_f32_e32 v156, v156, v67
	v_sub_f32_e32 v157, v157, v67
	v_sub_f32_e32 v104, v104, v67
	v_sub_f32_e32 v105, v105, v67
	v_sub_f32_e32 v106, v106, v67
	v_sub_f32_e32 v107, v107, v67
	v_sub_f32_e32 v92, v92, v67
	v_sub_f32_e32 v93, v93, v67
	v_sub_f32_e32 v94, v94, v67
	v_sub_f32_e32 v95, v95, v67
	v_mul_f32_e32 v158, v158, v68
	v_mov_b32_e32 v67, v66
	v_mov_b32_e32 v68, v66
	v_mov_b32_e32 v69, v66
	v_mov_b32_e32 v70, v66
	v_mov_b32_e32 v71, v66
	v_mov_b32_e32 v72, v66
	v_mov_b32_e32 v73, v66
	v_mov_b32_e32 v74, v66
	v_mov_b32_e32 v75, v66
	v_mov_b32_e32 v76, v66
	v_mov_b32_e32 v77, v66
	v_mov_b32_e32 v78, v66
	v_mov_b32_e32 v79, v66
	v_mov_b32_e32 v80, v66
	v_mov_b32_e32 v81, v66
	s_branch .LBB0_587

; #define LAS __attribute__((address_space(3)))
; __device__ __forceinline__ float max3f(float a, float b, float c) { float r; asm("v_max3_f32 %0, %1, %2, %3" : "=v"(r) : "v"(a), "v"(b), "v"(c)); return r; }
; template <int DQK, int DV, bool BIAS> ...
;     ...
;         const LAS unsigned char* kb = lds + buf * KBUF + r32 * KP + hi * 16;
; #pragma unroll
;         for (int ks = 0; ks < NKS; ++ks) {
;             const bf16x8 k0 = *(const LAS bf16x8*)(kb + ks * 32), k1 = *(const LAS bf16x8*)(kb + 32 * KP + ks * 32);
;             if (ks == 0) { p0 = __builtin_amdgcn_mfma_f32_32x32x16_bf16(k0, qf[0], negm, 0, 0, 0); p1 = __builtin_amdgcn_mfma_f32_32x32x16_bf16(k1, qf[0], negm, 0, 0, 0); }
;             else { p0 = __builtin_amdgcn_mfma_f32_32x32x16_bf16(k0, qf[ks], p0, 0, 0, 0); p1 = __builtin_amdgcn_mfma_f32_32x32x16_bf16(k1, qf[ks], p1, 0, 0, 0); }
;         }
;         if (BIAS) {
;             asm volatile("s_nop 15\n\ts_nop 7" : "+v"(p0), "+v"(p1));
;             const float d0 = qp - (float)(t * 64 + 4 * hi);
; #pragma unroll
;             for (int r = 0; r < 16; ++r) { const float dk = d0 - (float)((r & 3) + 8 * (r >> 2)); p0[r] = p0[r] - sl2 * fabsf(dk); p1[r] = p1[r] - sl2 * fabsf(dk - 32.f); }
;         } else {
;             asm volatile("s_nop 15\n\ts_nop 7" : "+v"(p0), "+v"(p1));
;         }
;         float mxa = max3f(p0[0], p0[1], p1[0]), mxb = max3f(p0[2], p0[3], p1[1]); mxa = max3f(mxa, p1[2], p1[3]);
; #pragma unroll
;         for (int r = 4; r < 16; r += 4) { mxa = max3f(mxa, p0[r], p0[r + 1]); mxb = max3f(mxb, p0[r + 2], p0[r + 3]); mxa = max3f(mxa, p1[r], p1[r + 1]); mxb = max3f(mxb, p1[r + 2], p1[r + 3]); }
;         float mx = fmaxf(mxa, mxb);
;         if (__any(mx > 8.f)) {
;             mx = fmaxf(mx, __shfl_xor(mx, 32));
;             const float dl = fmaxf(mx, 0.f); mhat += dl;
;             const float f = __builtin_amdgcn_exp2f(-dl);
; #pragma unroll
;             for (int r = 0; r < 16; ++r) { p0[r] -= dl; p1[r] -= dl; negm[r] = -mhat; }
;             l *= f;
; #pragma unroll
;             for (int d = 0; d < NDT; ++d)
; #pragma unroll
;                 for (int r = 0; r < 16; ++r) o[d][r] *= f;
;         }
.LBB0_604:
	ds_read_b128 v[34:37], v130
	ds_read_b128 v[38:41], v130 offset:32
	s_waitcnt lgkmcnt(1)
	v_mfma_f32_32x32x16_bf16 v[82:97], v[34:37], v[98:101], v[50:65]
	ds_read_b128 v[34:37], v130 offset:4608
	ds_read_b128 v[42:45], v130 offset:4640
	s_waitcnt lgkmcnt(1)
	v_mfma_f32_32x32x16_bf16 v[66:81], v[34:37], v[98:101], v[50:65]
	v_mfma_f32_32x32x16_bf16 v[82:97], v[38:41], v[102:105], v[82:97]
	ds_read_b128 v[34:37], v130 offset:64
	ds_read_b128 v[38:41], v130 offset:96
	s_waitcnt lgkmcnt(2)
	v_mfma_f32_32x32x16_bf16 v[66:81], v[42:45], v[102:105], v[66:81]
	s_waitcnt lgkmcnt(1)
	v_mfma_f32_32x32x16_bf16 v[82:97], v[34:37], v[106:109], v[82:97]
	ds_read_b128 v[34:37], v130 offset:4672
	ds_read_b128 v[42:45], v130 offset:4704
	s_waitcnt lgkmcnt(1)
	v_mfma_f32_32x32x16_bf16 v[66:81], v[34:37], v[106:109], v[66:81]
	v_mfma_f32_32x32x16_bf16 v[82:97], v[38:41], v[110:113], v[82:97]
	s_waitcnt lgkmcnt(0)
	v_mfma_f32_32x32x16_bf16 v[66:81], v[42:45], v[110:113], v[66:81]
	s_nop 15
	s_nop 7
	s_nop 0
	v_max3_f32 v34, v82, v83, v66
	v_max3_f32 v35, v84, v85, v67
	v_max3_f32 v34, v34, v68, v69
	v_max3_f32 v35, v35, v88, v89
	v_max3_f32 v34, v34, v86, v87
	v_max3_f32 v35, v35, v72, v73
	v_max3_f32 v34, v34, v70, v71
	v_max3_f32 v35, v35, v92, v93
	v_max3_f32 v34, v34, v90, v91
	v_max3_f32 v35, v35, v76, v77
	v_max3_f32 v34, v34, v74, v75
	v_max3_f32 v35, v35, v96, v97
	v_max3_f32 v34, v34, v94, v95
	v_max3_f32 v35, v35, v80, v81
	v_max3_f32 v34, v34, v78, v79
	v_max_f32_e32 v35, v35, v35
	v_max_f32_e32 v34, v34, v34
	v_max_f32_e32 v34, v34, v35
	v_cmp_lt_f32_e32 vcc, s47, v34
	s_cbranch_vccz .LBB0_606
	ds_bpermute_b32 v35, v168, v34
	s_waitcnt lgkmcnt(0)
	v_max3_f32 v36, v34, v35, 0
	v_exp_f32_e64 v38, -v36
	v_add_f32_e32 v143, v143, v36
	v_xor_b32_e32 v34, 0x80000000, v143
	v_pk_add_f32 v[82:83], v[82:83], v[36:37] op_sel_hi:[1,0] neg_lo:[0,1] neg_hi:[0,1]
	v_pk_add_f32 v[66:67], v[66:67], v[36:37] op_sel_hi:[1,0] neg_lo:[0,1] neg_hi:[0,1]
	v_pk_add_f32 v[84:85], v[84:85], v[36:37] op_sel_hi:[1,0] neg_lo:[0,1] neg_hi:[0,1]
	v_pk_add_f32 v[68:69], v[68:69], v[36:37] op_sel_hi:[1,0] neg_lo:[0,1] neg_hi:[0,1]
	v_pk_add_f32 v[86:87], v[86:87], v[36:37] op_sel_hi:[1,0] neg_lo:[0,1] neg_hi:[0,1]
	v_pk_add_f32 v[70:71], v[70:71], v[36:37] op_sel_hi:[1,0] neg_lo:[0,1] neg_hi:[0,1]
	v_pk_add_f32 v[88:89], v[88:89], v[36:37] op_sel_hi:[1,0] neg_lo:[0,1] neg_hi:[0,1]
	v_pk_add_f32 v[72:73], v[72:73], v[36:37] op_sel_hi:[1,0] neg_lo:[0,1] neg_hi:[0,1]
	v_pk_add_f32 v[90:91], v[90:91], v[36:37] op_sel_hi:[1,0] neg_lo:[0,1] neg_hi:[0,1]
	v_pk_add_f32 v[74:75], v[74:75], v[36:37] op_sel_hi:[1,0] neg_lo:[0,1] neg_hi:[0,1]
	v_pk_add_f32 v[92:93], v[92:93], v[36:37] op_sel_hi:[1,0] neg_lo:[0,1] neg_hi:[0,1]
	v_pk_add_f32 v[76:77], v[76:77], v[36:37] op_sel_hi:[1,0] neg_lo:[0,1] neg_hi:[0,1]
	v_pk_add_f32 v[94:95], v[94:95], v[36:37] op_sel_hi:[1,0] neg_lo:[0,1] neg_hi:[0,1]
	v_pk_add_f32 v[78:79], v[78:79], v[36:37] op_sel_hi:[1,0] neg_lo:[0,1] neg_hi:[0,1]
	v_pk_add_f32 v[96:97], v[96:97], v[36:37] op_sel_hi:[1,0] neg_lo:[0,1] neg_hi:[0,1]
	v_pk_add_f32 v[80:81], v[80:81], v[36:37] op_sel_hi:[1,0] neg_lo:[0,1] neg_hi:[0,1]
	v_pk_mul_f32 v[16:17], v[16:17], v[38:39] op_sel_hi:[1,0]
	v_pk_mul_f32 v[14:15], v[14:15], v[38:39] op_sel_hi:[1,0]
	v_pk_mul_f32 v[12:13], v[12:13], v[38:39] op_sel_hi:[1,0]
	v_pk_mul_f32 v[10:11], v[10:11], v[38:39] op_sel_hi:[1,0]
	v_pk_mul_f32 v[8:9], v[8:9], v[38:39] op_sel_hi:[1,0]
	v_pk_mul_f32 v[6:7], v[6:7], v[38:39] op_sel_hi:[1,0]
	v_pk_mul_f32 v[4:5], v[4:5], v[38:39] op_sel_hi:[1,0]
	v_pk_mul_f32 v[2:3], v[2:3], v[38:39] op_sel_hi:[1,0]
	v_pk_mul_f32 v[32:33], v[32:33], v[38:39] op_sel_hi:[1,0]
	v_pk_mul_f32 v[30:31], v[30:31], v[38:39] op_sel_hi:[1,0]
	v_pk_mul_f32 v[28:29], v[28:29], v[38:39] op_sel_hi:[1,0]
	v_pk_mul_f32 v[26:27], v[26:27], v[38:39] op_sel_hi:[1,0]
	v_pk_mul_f32 v[24:25], v[24:25], v[38:39] op_sel_hi:[1,0]
	v_pk_mul_f32 v[22:23], v[22:23], v[38:39] op_sel_hi:[1,0]
	v_pk_mul_f32 v[20:21], v[20:21], v[38:39] op_sel_hi:[1,0]
	v_pk_mul_f32 v[18:19], v[18:19], v[38:39] op_sel_hi:[1,0]
	v_mul_f32_e32 v144, v144, v38
	v_mov_b32_e32 v35, v34
	v_mov_b32_e32 v36, v34
	v_mov_b32_e32 v37, v34
	v_mov_b32_e32 v38, v34
	v_mov_b32_e32 v39, v34
	v_mov_b32_e32 v40, v34
	v_mov_b32_e32 v41, v34
	v_mov_b32_e32 v42, v34
	v_mov_b32_e32 v43, v34
	v_mov_b32_e32 v44, v34
	v_mov_b32_e32 v45, v34
	v_mov_b32_e32 v46, v34
	v_mov_b32_e32 v47, v34
	v_mov_b32_e32 v48, v34
	v_mov_b32_e32 v49, v34
	v_mov_b32_e32 v50, v34
	v_mov_b32_e32 v51, v34
	v_mov_b32_e32 v52, v34
	v_mov_b32_e32 v53, v34
	v_mov_b32_e32 v54, v34
	v_mov_b32_e32 v55, v34
	v_mov_b32_e32 v56, v34
	v_mov_b32_e32 v57, v34
	v_mov_b32_e32 v58, v34
	v_mov_b32_e32 v59, v34
	v_mov_b32_e32 v60, v34
	v_mov_b32_e32 v61, v34
	v_mov_b32_e32 v62, v34
	v_mov_b32_e32 v63, v34
	v_mov_b32_e32 v64, v34
	v_mov_b32_e32 v65, v34
	s_branch .LBB0_607

; #define LAS __attribute__((address_space(3)))
; template <int DQK, int DV, bool BIAS> ...
;     ...
;         const LAS unsigned char* kb = lds + buf * KBUF + r32 * KP + hi * 16;
; #pragma unroll
;         for (int ks = 0; ks < NKS; ++ks) {
;             const bf16x8 k0 = *(const LAS bf16x8*)(kb + ks * 32), k1 = *(const LAS bf16x8*)(kb + 32 * KP + ks * 32);
;             if (ks == 0) { p0 = __builtin_amdgcn_mfma_f32_32x32x16_bf16(k0, qf[0], negm, 0, 0, 0); p1 = __builtin_amdgcn_mfma_f32_32x32x16_bf16(k1, qf[0], negm, 0, 0, 0); }
;             else { p0 = __builtin_amdgcn_mfma_f32_32x32x16_bf16(k0, qf[ks], p0, 0, 0, 0); p1 = __builtin_amdgcn_mfma_f32_32x32x16_bf16(k1, qf[ks], p1, 0, 0, 0); }
;         }
;         if (BIAS) {
;             asm volatile("s_nop 15\n\ts_nop 7" : "+v"(p0), "+v"(p1));
;             const float d0 = qp - (float)(t * 64 + 4 * hi);
; #pragma unroll
;             for (int r = 0; r < 16; ++r) { const float dk = d0 - (float)((r & 3) + 8 * (r >> 2)); p0[r] = p0[r] - sl2 * fabsf(dk); p1[r] = p1[r] - sl2 * fabsf(dk - 32.f); }
;         } else {
;             asm volatile("s_nop 15\n\ts_nop 7" : "+v"(p0), "+v"(p1));
;         }
;     ...
;             const LAS unsigned char* vbase = lds + VOFF + vcur * VBUF + (4 * hi + ((lane & 15) >> 2)) * 64 + ((lane >> 4) & 1) * 32 + (lane & 3) * 8;
;             float ls = 0.f;
; #pragma unroll
;             for (int hs = 0; hs < 4; ++hs) {
;                 float e[8];
; #pragma unroll
;                 for (int j = 0; j < 8; ++j) { e[j] = __builtin_amdgcn_exp2f(hs < 2 ? p0[8 * (hs & 1) + j] : p1[8 * (hs & 1) + j]); ls += e[j]; }
;                 pw[hs].x = cvtpk(e[0], e[1]); pw[hs].y = cvtpk(e[2], e[3]); pw[hs].z = cvtpk(e[4], e[5]); pw[hs].w = cvtpk(e[6], e[7]);
;                 const bf16x8 pbv = __builtin_bit_cast(bf16x8, pw[hs]);
; #pragma unroll
;                 for (int d = 0; d < NDT; ++d) { const LAS unsigned char* vp = vbase + d * 4096 + hs * 1024;
;                     const v4i16_t a0 = __builtin_amdgcn_ds_read_tr16_b64_v4i16((LAS v4i16_t*)vp), a1 = __builtin_amdgcn_ds_read_tr16_b64_v4i16((LAS v4i16_t*)(vp + 512));
;                     const bf16x8 av = {a0[0], a0[1], a0[2], a0[3], a1[0], a1[1], a1[2], a1[3]};
;                     o[d] = __builtin_amdgcn_mfma_f32_32x32x16_bf16(av, pbv, o[d], 0, 0, 0); }
;                 __builtin_amdgcn_sched_barrier(0);
;             }
;             l += ls;
.LBB0_607:
	v_exp_f32_e32 v145, v82
	v_exp_f32_e32 v147, v83
	v_exp_f32_e32 v152, v84
	v_exp_f32_e32 v153, v85
	v_exp_f32_e32 v154, v86
	v_exp_f32_e32 v155, v87
	ds_read_b64_tr_b16 v[82:83], v141 offset:36864
	ds_read_b64_tr_b16 v[84:85], v141 offset:37376
	v_exp_f32_e32 v156, v88
	v_exp_f32_e32 v157, v89
	ds_read_b64_tr_b16 v[148:149], v141 offset:40960
	ds_read_b64_tr_b16 v[150:151], v141 offset:41472
	v_cvt_pk_bf16_f32 v86, v145, v147
	v_cvt_pk_bf16_f32 v87, v152, v153
	v_cvt_pk_bf16_f32 v88, v154, v155
	v_cvt_pk_bf16_f32 v89, v156, v157
	s_waitcnt lgkmcnt(2)
	s_nop 0
	v_mfma_f32_32x32x16_bf16 v[18:33], v[82:85], v[86:89], v[18:33]
	v_add_f32_e32 v82, 0, v145
	v_add_f32_e32 v82, v147, v82
	v_add_f32_e32 v82, v152, v82
	v_add_f32_e32 v82, v153, v82
	v_add_f32_e32 v82, v154, v82
	v_add_f32_e32 v82, v155, v82
	v_add_f32_e32 v82, v156, v82
	s_waitcnt lgkmcnt(0)
	v_mfma_f32_32x32x16_bf16 v[2:17], v[148:151], v[86:89], v[2:17]
	v_add_f32_e32 v145, v157, v82
	v_exp_f32_e32 v147, v90
	v_exp_f32_e32 v148, v91
	v_exp_f32_e32 v149, v92
	v_exp_f32_e32 v150, v93
	v_exp_f32_e32 v94, v94
	v_exp_f32_e32 v95, v95
	ds_read_b64_tr_b16 v[82:83], v141 offset:37888
	ds_read_b64_tr_b16 v[84:85], v141 offset:38400
	v_exp_f32_e32 v96, v96
	v_exp_f32_e32 v97, v97
	ds_read_b64_tr_b16 v[90:91], v141 offset:41984
	ds_read_b64_tr_b16 v[92:93], v141 offset:42496
	v_cvt_pk_bf16_f32 v86, v147, v148
	v_cvt_pk_bf16_f32 v87, v149, v150
	v_cvt_pk_bf16_f32 v88, v94, v95
	v_cvt_pk_bf16_f32 v89, v96, v97
	s_waitcnt lgkmcnt(2)
	s_nop 0
	v_mfma_f32_32x32x16_bf16 v[18:33], v[82:85], v[86:89], v[18:33]
	v_add_f32_e32 v82, v147, v145
	v_add_f32_e32 v82, v148, v82
	v_add_f32_e32 v82, v149, v82
	v_add_f32_e32 v82, v150, v82
	v_add_f32_e32 v82, v94, v82
	v_add_f32_e32 v82, v95, v82
	v_add_f32_e32 v82, v96, v82
	s_waitcnt lgkmcnt(0)
	v_mfma_f32_32x32x16_bf16 v[2:17], v[90:93], v[86:89], v[2:17]
	v_add_f32_e32 v86, v97, v82
	v_exp_f32_e32 v87, v66
	v_exp_f32_e32 v88, v67
	v_exp_f32_e32 v89, v68
	v_exp_f32_e32 v90, v69
	v_exp_f32_e32 v91, v70
	v_exp_f32_e32 v92, v71
	ds_read_b64_tr_b16 v[66:67], v141 offset:38912
	ds_read_b64_tr_b16 v[68:69], v141 offset:39424
	v_exp_f32_e32 v93, v72
	v_exp_f32_e32 v94, v73
	ds_read_b64_tr_b16 v[82:83], v141 offset:43008
	ds_read_b64_tr_b16 v[84:85], v141 offset:43520
	v_cvt_pk_bf16_f32 v70, v87, v88
	v_cvt_pk_bf16_f32 v71, v89, v90
	v_cvt_pk_bf16_f32 v72, v91, v92
	v_cvt_pk_bf16_f32 v73, v93, v94
	s_waitcnt lgkmcnt(2)
	s_nop 0
	v_mfma_f32_32x32x16_bf16 v[18:33], v[66:69], v[70:73], v[18:33]
	v_add_f32_e32 v66, v87, v86
	v_add_f32_e32 v66, v88, v66
	v_add_f32_e32 v66, v89, v66
	v_add_f32_e32 v66, v90, v66
	v_add_f32_e32 v66, v91, v66
	v_add_f32_e32 v66, v92, v66
	v_add_f32_e32 v66, v93, v66
	s_waitcnt lgkmcnt(0)
	v_mfma_f32_32x32x16_bf16 v[2:17], v[82:85], v[70:73], v[2:17]
	v_add_f32_e32 v82, v94, v66
	v_exp_f32_e32 v83, v74
	v_exp_f32_e32 v84, v75
	v_exp_f32_e32 v85, v76
	v_exp_f32_e32 v86, v77
	v_exp_f32_e32 v78, v78
	v_exp_f32_e32 v79, v79
	ds_read_b64_tr_b16 v[66:67], v141 offset:39936
	ds_read_b64_tr_b16 v[68:69], v141 offset:40448
	v_exp_f32_e32 v80, v80
	v_exp_f32_e32 v81, v81
	ds_read_b64_tr_b16 v[74:75], v141 offset:44032
	ds_read_b64_tr_b16 v[76:77], v141 offset:44544
	v_cvt_pk_bf16_f32 v70, v83, v84
	v_cvt_pk_bf16_f32 v71, v85, v86
	v_cvt_pk_bf16_f32 v72, v78, v79
	v_cvt_pk_bf16_f32 v73, v80, v81
	s_waitcnt lgkmcnt(2)
	s_nop 0
	v_mfma_f32_32x32x16_bf16 v[18:33], v[66:69], v[70:73], v[18:33]
	v_add_f32_e32 v66, v83, v82
	v_add_f32_e32 v66, v84, v66
	v_add_f32_e32 v66, v85, v66
	v_add_f32_e32 v66, v86, v66
	v_add_f32_e32 v66, v78, v66
	v_add_f32_e32 v66, v79, v66
	v_add_f32_e32 v66, v80, v66
	s_waitcnt lgkmcnt(0)
	v_mfma_f32_32x32x16_bf16 v[2:17], v[74:77], v[70:73], v[2:17]
	v_add_f32_e32 v145, v81, v66
	ds_read_b128 v[66:69], v130 offset:9216
	ds_read_b128 v[148:151], v130 offset:9248
	ds_read_b128 v[152:155], v130 offset:13824
	ds_read_b128 v[156:159], v130 offset:13856
	v_add_f32_e32 v144, v144, v145
	s_waitcnt lgkmcnt(3)
	v_mfma_f32_32x32x16_bf16 v[82:97], v[66:69], v[98:101], v[34:49]
	s_waitcnt lgkmcnt(1)
	v_mfma_f32_32x32x16_bf16 v[66:81], v[152:155], v[98:101], v[34:49]
	v_mfma_f32_32x32x16_bf16 v[82:97], v[148:151], v[102:105], v[82:97]
	ds_read_b128 v[148:151], v130 offset:9280
	ds_read_b128 v[152:155], v130 offset:9312
	s_waitcnt lgkmcnt(2)
	v_mfma_f32_32x32x16_bf16 v[66:81], v[156:159], v[102:105], v[66:81]
	s_waitcnt lgkmcnt(1)
	v_mfma_f32_32x32x16_bf16 v[82:97], v[148:151], v[106:109], v[82:97]
	ds_read_b128 v[148:151], v130 offset:13888
	ds_read_b128 v[156:159], v130 offset:13920
	s_waitcnt lgkmcnt(1)
	v_mfma_f32_32x32x16_bf16 v[66:81], v[148:151], v[106:109], v[66:81]
	v_mfma_f32_32x32x16_bf16 v[82:97], v[152:155], v[110:113], v[82:97]
	s_waitcnt lgkmcnt(0)
	v_mfma_f32_32x32x16_bf16 v[66:81], v[156:159], v[110:113], v[66:81]
	s_nop 15
	s_nop 7
	s_nop 0
	v_max3_f32 v145, v82, v83, v66
	v_max3_f32 v147, v84, v85, v67
	v_max3_f32 v145, v145, v68, v69
	v_max3_f32 v147, v147, v88, v89
	v_max3_f32 v145, v145, v86, v87
	v_max3_f32 v147, v147, v72, v73
	v_max3_f32 v145, v145, v70, v71
	v_max3_f32 v147, v147, v92, v93
	v_max3_f32 v145, v145, v90, v91
	v_max3_f32 v147, v147, v76, v77
	v_max3_f32 v145, v145, v74, v75
	v_max3_f32 v147, v147, v96, v97
	v_max3_f32 v145, v145, v94, v95
	v_max3_f32 v147, v147, v80, v81
	v_max3_f32 v145, v145, v78, v79
	v_max_f32_e32 v147, v147, v147
	v_max_f32_e32 v145, v145, v145
	v_max_f32_e32 v145, v145, v147
	v_cmp_lt_f32_e32 vcc, s47, v145
	s_cbranch_vccz .LBB0_609
; template <int DQK, int DV, bool BIAS> ...
;     ...
;         if (__any(mx > 8.f)) {
;             mx = fmaxf(mx, __shfl_xor(mx, 32));
;             const float dl = fmaxf(mx, 0.f); mhat += dl;
;             const float f = __builtin_amdgcn_exp2f(-dl);
; #pragma unroll
;             for (int r = 0; r < 16; ++r) { p0[r] -= dl; p1[r] -= dl; negm[r] = -mhat; }
;             l *= f;
; #pragma unroll
;             for (int d = 0; d < NDT; ++d)
; #pragma unroll
;                 for (int r = 0; r < 16; ++r) o[d][r] *= f;
;         }
	ds_bpermute_b32 v34, v168, v145
	s_waitcnt lgkmcnt(0)
	v_max3_f32 v36, v145, v34, 0
	v_exp_f32_e64 v38, -v36
	v_add_f32_e32 v143, v143, v36
	v_xor_b32_e32 v34, 0x80000000, v143
	v_pk_add_f32 v[82:83], v[82:83], v[36:37] op_sel_hi:[1,0] neg_lo:[0,1] neg_hi:[0,1]
	v_pk_add_f32 v[66:67], v[66:67], v[36:37] op_sel_hi:[1,0] neg_lo:[0,1] neg_hi:[0,1]
	v_pk_add_f32 v[84:85], v[84:85], v[36:37] op_sel_hi:[1,0] neg_lo:[0,1] neg_hi:[0,1]
	v_pk_add_f32 v[68:69], v[68:69], v[36:37] op_sel_hi:[1,0] neg_lo:[0,1] neg_hi:[0,1]
	v_pk_add_f32 v[86:87], v[86:87], v[36:37] op_sel_hi:[1,0] neg_lo:[0,1] neg_hi:[0,1]
	v_pk_add_f32 v[70:71], v[70:71], v[36:37] op_sel_hi:[1,0] neg_lo:[0,1] neg_hi:[0,1]
	v_pk_add_f32 v[88:89], v[88:89], v[36:37] op_sel_hi:[1,0] neg_lo:[0,1] neg_hi:[0,1]
	v_pk_add_f32 v[72:73], v[72:73], v[36:37] op_sel_hi:[1,0] neg_lo:[0,1] neg_hi:[0,1]
	v_pk_add_f32 v[90:91], v[90:91], v[36:37] op_sel_hi:[1,0] neg_lo:[0,1] neg_hi:[0,1]
	v_pk_add_f32 v[74:75], v[74:75], v[36:37] op_sel_hi:[1,0] neg_lo:[0,1] neg_hi:[0,1]
	v_pk_add_f32 v[92:93], v[92:93], v[36:37] op_sel_hi:[1,0] neg_lo:[0,1] neg_hi:[0,1]
	v_pk_add_f32 v[76:77], v[76:77], v[36:37] op_sel_hi:[1,0] neg_lo:[0,1] neg_hi:[0,1]
	v_pk_add_f32 v[94:95], v[94:95], v[36:37] op_sel_hi:[1,0] neg_lo:[0,1] neg_hi:[0,1]
	v_pk_add_f32 v[78:79], v[78:79], v[36:37] op_sel_hi:[1,0] neg_lo:[0,1] neg_hi:[0,1]
	v_pk_add_f32 v[96:97], v[96:97], v[36:37] op_sel_hi:[1,0] neg_lo:[0,1] neg_hi:[0,1]
	v_pk_add_f32 v[80:81], v[80:81], v[36:37] op_sel_hi:[1,0] neg_lo:[0,1] neg_hi:[0,1]
	v_pk_mul_f32 v[16:17], v[16:17], v[38:39] op_sel_hi:[1,0]
	v_pk_mul_f32 v[14:15], v[14:15], v[38:39] op_sel_hi:[1,0]
	v_pk_mul_f32 v[12:13], v[12:13], v[38:39] op_sel_hi:[1,0]
	v_pk_mul_f32 v[10:11], v[10:11], v[38:39] op_sel_hi:[1,0]
	v_pk_mul_f32 v[8:9], v[8:9], v[38:39] op_sel_hi:[1,0]
	v_pk_mul_f32 v[6:7], v[6:7], v[38:39] op_sel_hi:[1,0]
	v_pk_mul_f32 v[4:5], v[4:5], v[38:39] op_sel_hi:[1,0]
	v_pk_mul_f32 v[2:3], v[2:3], v[38:39] op_sel_hi:[1,0]
	v_pk_mul_f32 v[32:33], v[32:33], v[38:39] op_sel_hi:[1,0]
	v_pk_mul_f32 v[30:31], v[30:31], v[38:39] op_sel_hi:[1,0]
	v_pk_mul_f32 v[28:29], v[28:29], v[38:39] op_sel_hi:[1,0]
	v_pk_mul_f32 v[26:27], v[26:27], v[38:39] op_sel_hi:[1,0]
	v_pk_mul_f32 v[24:25], v[24:25], v[38:39] op_sel_hi:[1,0]
	v_pk_mul_f32 v[22:23], v[22:23], v[38:39] op_sel_hi:[1,0]
	v_pk_mul_f32 v[20:21], v[20:21], v[38:39] op_sel_hi:[1,0]
	v_pk_mul_f32 v[18:19], v[18:19], v[38:39] op_sel_hi:[1,0]
	v_mul_f32_e32 v144, v144, v38
	v_mov_b32_e32 v35, v34
	v_mov_b32_e32 v36, v34
	v_mov_b32_e32 v37, v34
	v_mov_b32_e32 v38, v34
	v_mov_b32_e32 v39, v34
	v_mov_b32_e32 v40, v34
	v_mov_b32_e32 v41, v34
	v_mov_b32_e32 v42, v34
	v_mov_b32_e32 v43, v34
	v_mov_b32_e32 v44, v34
	v_mov_b32_e32 v45, v34
	v_mov_b32_e32 v46, v34
	v_mov_b32_e32 v47, v34
	v_mov_b32_e32 v48, v34
	v_mov_b32_e32 v49, v34
	v_mov_b32_e32 v50, v34
	v_mov_b32_e32 v51, v34
	v_mov_b32_e32 v52, v34
	v_mov_b32_e32 v53, v34
	v_mov_b32_e32 v54, v34
	v_mov_b32_e32 v55, v34
	v_mov_b32_e32 v56, v34
	v_mov_b32_e32 v57, v34
	v_mov_b32_e32 v58, v34
	v_mov_b32_e32 v59, v34
	v_mov_b32_e32 v60, v34
	v_mov_b32_e32 v61, v34
	v_mov_b32_e32 v62, v34
	v_mov_b32_e32 v63, v34
	v_mov_b32_e32 v64, v34
	v_mov_b32_e32 v65, v34

; #define LAS __attribute__((address_space(3)))
; __device__ __forceinline__ float max3f(float a, float b, float c) { float r; asm("v_max3_f32 %0, %1, %2, %3" : "=v"(r) : "v"(a), "v"(b), "v"(c)); return r; }
; template <int DQK, int DV, bool BIAS> ...
;     ...
;         const LAS unsigned char* kb = lds + buf * KBUF + r32 * KP + hi * 16;
; #pragma unroll
;         for (int ks = 0; ks < NKS; ++ks) {
;             const bf16x8 k0 = *(const LAS bf16x8*)(kb + ks * 32), k1 = *(const LAS bf16x8*)(kb + 32 * KP + ks * 32);
;             if (ks == 0) { p0 = __builtin_amdgcn_mfma_f32_32x32x16_bf16(k0, qf[0], negm, 0, 0, 0); p1 = __builtin_amdgcn_mfma_f32_32x32x16_bf16(k1, qf[0], negm, 0, 0, 0); }
;             else { p0 = __builtin_amdgcn_mfma_f32_32x32x16_bf16(k0, qf[ks], p0, 0, 0, 0); p1 = __builtin_amdgcn_mfma_f32_32x32x16_bf16(k1, qf[ks], p1, 0, 0, 0); }
;         }
;         if (BIAS) {
;             asm volatile("s_nop 15\n\ts_nop 7" : "+v"(p0), "+v"(p1));
;             const float d0 = qp - (float)(t * 64 + 4 * hi);
; #pragma unroll
;             for (int r = 0; r < 16; ++r) { const float dk = d0 - (float)((r & 3) + 8 * (r >> 2)); p0[r] = p0[r] - sl2 * fabsf(dk); p1[r] = p1[r] - sl2 * fabsf(dk - 32.f); }
;         } else {
;             asm volatile("s_nop 15\n\ts_nop 7" : "+v"(p0), "+v"(p1));
;         }
;         float mxa = max3f(p0[0], p0[1], p1[0]), mxb = max3f(p0[2], p0[3], p1[1]); mxa = max3f(mxa, p1[2], p1[3]);
; #pragma unroll
;         for (int r = 4; r < 16; r += 4) { mxa = max3f(mxa, p0[r], p0[r + 1]); mxb = max3f(mxb, p0[r + 2], p0[r + 3]); mxa = max3f(mxa, p1[r], p1[r + 1]); mxb = max3f(mxb, p1[r + 2], p1[r + 3]); }
;         float mx = fmaxf(mxa, mxb);
;         if (__any(mx > 8.f)) {
;             mx = fmaxf(mx, __shfl_xor(mx, 32));
;             const float dl = fmaxf(mx, 0.f); mhat += dl;
;             const float f = __builtin_amdgcn_exp2f(-dl);
; #pragma unroll
;             for (int r = 0; r < 16; ++r) { p0[r] -= dl; p1[r] -= dl; negm[r] = -mhat; }
;             l *= f;
; #pragma unroll
;             for (int d = 0; d < NDT; ++d)
; #pragma unroll
;                 for (int r = 0; r < 16; ++r) o[d][r] *= f;
;         }
.LBB0_612:
	v_add_f32_e32 v150, 0, v150
	v_add_f32_e32 v150, v151, v150
	ds_read_b128 v[66:69], v130 offset:18432
	ds_read_b128 v[180:183], v130 offset:18464
	v_add_f32_e32 v145, v145, v150
	ds_read_b128 v[184:187], v130 offset:23040
	ds_read_b128 v[188:191], v130 offset:23072
	v_add_f32_e32 v145, v147, v145
	v_add_f32_e32 v145, v148, v145
	v_add_f32_e32 v145, v149, v145
	s_waitcnt lgkmcnt(3)
	v_mfma_f32_32x32x16_bf16 v[82:97], v[66:69], v[98:101], v[34:49]
	v_add_f32_e32 v145, v152, v145
	v_add_f32_e32 v145, v153, v145
	v_add_f32_e32 v145, v155, v145
	v_add_f32_e32 v145, v156, v145
	v_add_f32_e32 v145, v157, v145
	v_add_f32_e32 v145, v158, v145
	v_add_f32_e32 v145, v159, v145
	s_waitcnt lgkmcnt(1)
	v_mfma_f32_32x32x16_bf16 v[66:81], v[184:187], v[98:101], v[34:49]
	ds_read_b128 v[148:151], v130 offset:18496
	v_add_f32_e32 v145, v154, v145
	v_add_f32_e32 v145, v160, v145
	v_add_f32_e32 v145, v161, v145
	v_add_f32_e32 v145, v165, v145
	v_add_f32_e32 v145, v166, v145
	v_add_f32_e32 v145, v167, v145
	v_mfma_f32_32x32x16_bf16 v[82:97], v[180:183], v[102:105], v[82:97]
	ds_read_b128 v[156:159], v130 offset:23104
	ds_read_b128 v[180:183], v130 offset:18528
	v_add_f32_e32 v145, v162, v145
	v_add_f32_e32 v145, v163, v145
	v_add_f32_e32 v145, v164, v145
	v_add_f32_e32 v145, v169, v145
	v_add_f32_e32 v145, v170, v145
	v_add_f32_e32 v145, v175, v145
	s_waitcnt lgkmcnt(3)
	v_mfma_f32_32x32x16_bf16 v[66:81], v[188:191], v[102:105], v[66:81]
	v_add_f32_e32 v145, v176, v145
	v_add_f32_e32 v145, v171, v145
	v_add_f32_e32 v145, v172, v145
	v_add_f32_e32 v145, v173, v145
	v_add_f32_e32 v145, v174, v145
	v_add_f32_e32 v145, v177, v145
	v_add_f32_e32 v145, v178, v145
	s_waitcnt lgkmcnt(2)
	v_mfma_f32_32x32x16_bf16 v[82:97], v[148:151], v[106:109], v[82:97]
	ds_read_b128 v[148:151], v130 offset:23136
	v_add_f32_e32 v144, v144, v145
	s_waitcnt lgkmcnt(2)
	v_mfma_f32_32x32x16_bf16 v[66:81], v[156:159], v[106:109], v[66:81]
	s_waitcnt lgkmcnt(1)
	v_mfma_f32_32x32x16_bf16 v[82:97], v[180:183], v[110:113], v[82:97]
	s_waitcnt lgkmcnt(0)
	v_mfma_f32_32x32x16_bf16 v[66:81], v[148:151], v[110:113], v[66:81]
	s_nop 15
	s_nop 7
	s_nop 0
	v_max3_f32 v145, v82, v83, v66
	v_max3_f32 v147, v84, v85, v67
	v_max3_f32 v145, v145, v68, v69
	v_max3_f32 v147, v147, v88, v89
	v_max3_f32 v145, v145, v86, v87
	v_max3_f32 v147, v147, v72, v73
	v_max3_f32 v145, v145, v70, v71
	v_max3_f32 v147, v147, v92, v93
	v_max3_f32 v145, v145, v90, v91
	v_max3_f32 v147, v147, v76, v77
	v_max3_f32 v145, v145, v74, v75
	v_max3_f32 v147, v147, v96, v97
	v_max3_f32 v145, v145, v94, v95
	v_max3_f32 v147, v147, v80, v81
	v_max3_f32 v145, v145, v78, v79
	v_max_f32_e32 v147, v147, v147
	v_max_f32_e32 v145, v145, v145
	v_max_f32_e32 v145, v145, v147
	v_cmp_lt_f32_e32 vcc, s47, v145
	s_cbranch_vccz .LBB0_614
	ds_bpermute_b32 v34, v168, v145
	s_waitcnt lgkmcnt(0)
	v_max3_f32 v36, v145, v34, 0
	v_exp_f32_e64 v38, -v36
	v_add_f32_e32 v143, v143, v36
	v_xor_b32_e32 v34, 0x80000000, v143
	v_pk_add_f32 v[82:83], v[82:83], v[36:37] op_sel_hi:[1,0] neg_lo:[0,1] neg_hi:[0,1]
	v_pk_add_f32 v[66:67], v[66:67], v[36:37] op_sel_hi:[1,0] neg_lo:[0,1] neg_hi:[0,1]
	v_pk_add_f32 v[84:85], v[84:85], v[36:37] op_sel_hi:[1,0] neg_lo:[0,1] neg_hi:[0,1]
	v_pk_add_f32 v[68:69], v[68:69], v[36:37] op_sel_hi:[1,0] neg_lo:[0,1] neg_hi:[0,1]
	v_pk_add_f32 v[86:87], v[86:87], v[36:37] op_sel_hi:[1,0] neg_lo:[0,1] neg_hi:[0,1]
	v_pk_add_f32 v[70:71], v[70:71], v[36:37] op_sel_hi:[1,0] neg_lo:[0,1] neg_hi:[0,1]
	v_pk_add_f32 v[88:89], v[88:89], v[36:37] op_sel_hi:[1,0] neg_lo:[0,1] neg_hi:[0,1]
	v_pk_add_f32 v[72:73], v[72:73], v[36:37] op_sel_hi:[1,0] neg_lo:[0,1] neg_hi:[0,1]
	v_pk_add_f32 v[90:91], v[90:91], v[36:37] op_sel_hi:[1,0] neg_lo:[0,1] neg_hi:[0,1]
	v_pk_add_f32 v[74:75], v[74:75], v[36:37] op_sel_hi:[1,0] neg_lo:[0,1] neg_hi:[0,1]
	v_pk_add_f32 v[92:93], v[92:93], v[36:37] op_sel_hi:[1,0] neg_lo:[0,1] neg_hi:[0,1]
	v_pk_add_f32 v[76:77], v[76:77], v[36:37] op_sel_hi:[1,0] neg_lo:[0,1] neg_hi:[0,1]
	v_pk_add_f32 v[94:95], v[94:95], v[36:37] op_sel_hi:[1,0] neg_lo:[0,1] neg_hi:[0,1]
	v_pk_add_f32 v[78:79], v[78:79], v[36:37] op_sel_hi:[1,0] neg_lo:[0,1] neg_hi:[0,1]
	v_pk_add_f32 v[96:97], v[96:97], v[36:37] op_sel_hi:[1,0] neg_lo:[0,1] neg_hi:[0,1]
	v_pk_add_f32 v[80:81], v[80:81], v[36:37] op_sel_hi:[1,0] neg_lo:[0,1] neg_hi:[0,1]
	v_pk_mul_f32 v[16:17], v[16:17], v[38:39] op_sel_hi:[1,0]
	v_pk_mul_f32 v[14:15], v[14:15], v[38:39] op_sel_hi:[1,0]
	v_pk_mul_f32 v[12:13], v[12:13], v[38:39] op_sel_hi:[1,0]
	v_pk_mul_f32 v[10:11], v[10:11], v[38:39] op_sel_hi:[1,0]
	v_pk_mul_f32 v[8:9], v[8:9], v[38:39] op_sel_hi:[1,0]
	v_pk_mul_f32 v[6:7], v[6:7], v[38:39] op_sel_hi:[1,0]
	v_pk_mul_f32 v[4:5], v[4:5], v[38:39] op_sel_hi:[1,0]
	v_pk_mul_f32 v[2:3], v[2:3], v[38:39] op_sel_hi:[1,0]
	v_pk_mul_f32 v[32:33], v[32:33], v[38:39] op_sel_hi:[1,0]
	v_pk_mul_f32 v[30:31], v[30:31], v[38:39] op_sel_hi:[1,0]
	v_pk_mul_f32 v[28:29], v[28:29], v[38:39] op_sel_hi:[1,0]
	v_pk_mul_f32 v[26:27], v[26:27], v[38:39] op_sel_hi:[1,0]
	v_pk_mul_f32 v[24:25], v[24:25], v[38:39] op_sel_hi:[1,0]
	v_pk_mul_f32 v[22:23], v[22:23], v[38:39] op_sel_hi:[1,0]
	v_pk_mul_f32 v[20:21], v[20:21], v[38:39] op_sel_hi:[1,0]
	v_pk_mul_f32 v[18:19], v[18:19], v[38:39] op_sel_hi:[1,0]
	v_mul_f32_e32 v144, v144, v38
	v_mov_b32_e32 v35, v34
	v_mov_b32_e32 v36, v34
	v_mov_b32_e32 v37, v34
	v_mov_b32_e32 v38, v34
	v_mov_b32_e32 v39, v34
	v_mov_b32_e32 v40, v34
	v_mov_b32_e32 v41, v34
	v_mov_b32_e32 v42, v34
	v_mov_b32_e32 v43, v34
	v_mov_b32_e32 v44, v34
	v_mov_b32_e32 v45, v34
	v_mov_b32_e32 v46, v34
	v_mov_b32_e32 v47, v34
	v_mov_b32_e32 v48, v34
	v_mov_b32_e32 v49, v34
	v_mov_b32_e32 v50, v34
	v_mov_b32_e32 v51, v34
	v_mov_b32_e32 v52, v34
	v_mov_b32_e32 v53, v34
	v_mov_b32_e32 v54, v34
	v_mov_b32_e32 v55, v34
	v_mov_b32_e32 v56, v34
	v_mov_b32_e32 v57, v34
	v_mov_b32_e32 v58, v34
	v_mov_b32_e32 v59, v34
	v_mov_b32_e32 v60, v34
	v_mov_b32_e32 v61, v34
	v_mov_b32_e32 v62, v34
	v_mov_b32_e32 v63, v34
	v_mov_b32_e32 v64, v34
	v_mov_b32_e32 v65, v34
; #define LAS __attribute__((address_space(3)))
; template <int DQK, int DV, bool BIAS> ...
;     ...
;         const LAS unsigned char* kb = lds + buf * KBUF + r32 * KP + hi * 16;
; #pragma unroll
;         for (int ks = 0; ks < NKS; ++ks) {
;             const bf16x8 k0 = *(const LAS bf16x8*)(kb + ks * 32), k1 = *(const LAS bf16x8*)(kb + 32 * KP + ks * 32);
;             if (ks == 0) { p0 = __builtin_amdgcn_mfma_f32_32x32x16_bf16(k0, qf[0], negm, 0, 0, 0); p1 = __builtin_amdgcn_mfma_f32_32x32x16_bf16(k1, qf[0], negm, 0, 0, 0); }
;             else { p0 = __builtin_amdgcn_mfma_f32_32x32x16_bf16(k0, qf[ks], p0, 0, 0, 0); p1 = __builtin_amdgcn_mfma_f32_32x32x16_bf16(k1, qf[ks], p1, 0, 0, 0); }
;         }
;         if (BIAS) {
;             asm volatile("s_nop 15\n\ts_nop 7" : "+v"(p0), "+v"(p1));
;             const float d0 = qp - (float)(t * 64 + 4 * hi);
; #pragma unroll
;             for (int r = 0; r < 16; ++r) { const float dk = d0 - (float)((r & 3) + 8 * (r >> 2)); p0[r] = p0[r] - sl2 * fabsf(dk); p1[r] = p1[r] - sl2 * fabsf(dk - 32.f); }
;         } else {
;             asm volatile("s_nop 15\n\ts_nop 7" : "+v"(p0), "+v"(p1));
;         }
;     ...
;             const LAS unsigned char* vbase = lds + VOFF + vcur * VBUF + (4 * hi + ((lane & 15) >> 2)) * 64 + ((lane >> 4) & 1) * 32 + (lane & 3) * 8;
;             float ls = 0.f;
; #pragma unroll
;             for (int hs = 0; hs < 4; ++hs) {
;                 float e[8];
; #pragma unroll
;                 for (int j = 0; j < 8; ++j) { e[j] = __builtin_amdgcn_exp2f(hs < 2 ? p0[8 * (hs & 1) + j] : p1[8 * (hs & 1) + j]); ls += e[j]; }
;                 pw[hs].x = cvtpk(e[0], e[1]); pw[hs].y = cvtpk(e[2], e[3]); pw[hs].z = cvtpk(e[4], e[5]); pw[hs].w = cvtpk(e[6], e[7]);
;                 const bf16x8 pbv = __builtin_bit_cast(bf16x8, pw[hs]);
; #pragma unroll
;                 for (int d = 0; d < NDT; ++d) { const LAS unsigned char* vp = vbase + d * 4096 + hs * 1024;
;                     const v4i16_t a0 = __builtin_amdgcn_ds_read_tr16_b64_v4i16((LAS v4i16_t*)vp), a1 = __builtin_amdgcn_ds_read_tr16_b64_v4i16((LAS v4i16_t*)(vp + 512));
;                     const bf16x8 av = {a0[0], a0[1], a0[2], a0[3], a1[0], a1[1], a1[2], a1[3]};
;                     o[d] = __builtin_amdgcn_mfma_f32_32x32x16_bf16(av, pbv, o[d], 0, 0, 0); }
;                 __builtin_amdgcn_sched_barrier(0);
;             }
;             l += ls;
.LBB0_614:
	v_exp_f32_e32 v145, v82
	v_exp_f32_e32 v147, v83
	v_exp_f32_e32 v152, v84
	v_exp_f32_e32 v153, v85
	v_exp_f32_e32 v154, v86
	v_exp_f32_e32 v155, v87
	ds_read_b64_tr_b16 v[82:83], v141 offset:53248
	ds_read_b64_tr_b16 v[84:85], v141 offset:53760
	v_exp_f32_e32 v156, v88
	v_exp_f32_e32 v157, v89
	ds_read_b64_tr_b16 v[148:149], v141 offset:57344
	ds_read_b64_tr_b16 v[150:151], v141 offset:57856
	v_cvt_pk_bf16_f32 v86, v145, v147
	v_cvt_pk_bf16_f32 v87, v152, v153
	v_cvt_pk_bf16_f32 v88, v154, v155
	v_cvt_pk_bf16_f32 v89, v156, v157
	s_waitcnt lgkmcnt(2)
	s_nop 0
	v_mfma_f32_32x32x16_bf16 v[18:33], v[82:85], v[86:89], v[18:33]
	v_add_f32_e32 v82, 0, v145
	v_add_f32_e32 v82, v147, v82
	v_add_f32_e32 v82, v152, v82
	v_add_f32_e32 v82, v153, v82
	v_add_f32_e32 v82, v154, v82
	v_add_f32_e32 v82, v155, v82
	v_add_f32_e32 v82, v156, v82
	s_waitcnt lgkmcnt(0)
	v_mfma_f32_32x32x16_bf16 v[2:17], v[148:151], v[86:89], v[2:17]
	v_add_f32_e32 v145, v157, v82
	v_exp_f32_e32 v147, v90
	v_exp_f32_e32 v148, v91
	v_exp_f32_e32 v149, v92
	v_exp_f32_e32 v150, v93
	v_exp_f32_e32 v94, v94
	v_exp_f32_e32 v95, v95
	ds_read_b64_tr_b16 v[82:83], v141 offset:54272
	ds_read_b64_tr_b16 v[84:85], v141 offset:54784
	v_exp_f32_e32 v96, v96
	v_exp_f32_e32 v97, v97
	ds_read_b64_tr_b16 v[90:91], v141 offset:58368
	ds_read_b64_tr_b16 v[92:93], v141 offset:58880
	v_cvt_pk_bf16_f32 v86, v147, v148
	v_cvt_pk_bf16_f32 v87, v149, v150
	v_cvt_pk_bf16_f32 v88, v94, v95
	v_cvt_pk_bf16_f32 v89, v96, v97
	s_waitcnt lgkmcnt(2)
	s_nop 0
	v_mfma_f32_32x32x16_bf16 v[18:33], v[82:85], v[86:89], v[18:33]
	v_add_f32_e32 v82, v147, v145
	v_add_f32_e32 v82, v148, v82
	v_add_f32_e32 v82, v149, v82
	v_add_f32_e32 v82, v150, v82
	v_add_f32_e32 v82, v94, v82
	v_add_f32_e32 v82, v95, v82
	v_add_f32_e32 v82, v96, v82
	s_waitcnt lgkmcnt(0)
	v_mfma_f32_32x32x16_bf16 v[2:17], v[90:93], v[86:89], v[2:17]
	v_add_f32_e32 v86, v97, v82
	v_exp_f32_e32 v87, v66
	v_exp_f32_e32 v88, v67
	v_exp_f32_e32 v89, v68
	v_exp_f32_e32 v90, v69
	v_exp_f32_e32 v91, v70
	v_exp_f32_e32 v92, v71
	ds_read_b64_tr_b16 v[66:67], v141 offset:55296
	ds_read_b64_tr_b16 v[68:69], v141 offset:55808
	v_exp_f32_e32 v93, v72
	v_exp_f32_e32 v94, v73
	ds_read_b64_tr_b16 v[82:83], v141 offset:59392
	ds_read_b64_tr_b16 v[84:85], v141 offset:59904
	v_cvt_pk_bf16_f32 v70, v87, v88
	v_cvt_pk_bf16_f32 v71, v89, v90
	v_cvt_pk_bf16_f32 v72, v91, v92
	v_cvt_pk_bf16_f32 v73, v93, v94
	s_waitcnt lgkmcnt(2)
	s_nop 0
	v_mfma_f32_32x32x16_bf16 v[18:33], v[66:69], v[70:73], v[18:33]
	v_add_f32_e32 v66, v87, v86
	v_add_f32_e32 v66, v88, v66
	v_add_f32_e32 v66, v89, v66
	v_add_f32_e32 v66, v90, v66
	v_add_f32_e32 v66, v91, v66
	v_add_f32_e32 v66, v92, v66
	v_add_f32_e32 v66, v93, v66
	s_waitcnt lgkmcnt(0)
	v_mfma_f32_32x32x16_bf16 v[2:17], v[82:85], v[70:73], v[2:17]
	v_add_f32_e32 v82, v94, v66
	v_exp_f32_e32 v83, v74
	v_exp_f32_e32 v84, v75
	v_exp_f32_e32 v85, v76
	v_exp_f32_e32 v86, v77
	v_exp_f32_e32 v78, v78
	v_exp_f32_e32 v79, v79
	ds_read_b64_tr_b16 v[66:67], v141 offset:56320
	ds_read_b64_tr_b16 v[68:69], v141 offset:56832
	v_exp_f32_e32 v80, v80
	v_exp_f32_e32 v81, v81
	ds_read_b64_tr_b16 v[74:75], v141 offset:60416
	ds_read_b64_tr_b16 v[76:77], v141 offset:60928
	v_cvt_pk_bf16_f32 v70, v83, v84
	v_cvt_pk_bf16_f32 v71, v85, v86
	v_cvt_pk_bf16_f32 v72, v78, v79
	v_cvt_pk_bf16_f32 v73, v80, v81
	s_waitcnt lgkmcnt(2)
	s_nop 0
	v_mfma_f32_32x32x16_bf16 v[18:33], v[66:69], v[70:73], v[18:33]
	v_add_f32_e32 v66, v83, v82
	v_add_f32_e32 v66, v84, v66
	v_add_f32_e32 v66, v85, v66
	v_add_f32_e32 v66, v86, v66
	v_add_f32_e32 v66, v78, v66
	v_add_f32_e32 v66, v79, v66
	v_add_f32_e32 v66, v80, v66
	s_waitcnt lgkmcnt(0)
	v_mfma_f32_32x32x16_bf16 v[2:17], v[74:77], v[70:73], v[2:17]
	v_add_f32_e32 v94, v81, v66
	ds_read_b128 v[82:85], v130 offset:27648
	ds_read_b128 v[86:89], v130 offset:27680
	s_waitcnt lgkmcnt(1)
	v_mfma_f32_32x32x16_bf16 v[66:81], v[82:85], v[98:101], v[34:49]
	ds_read_b128 v[82:85], v130 offset:32256
	ds_read_b128 v[90:93], v130 offset:32288
	s_waitcnt lgkmcnt(1)
	v_mfma_f32_32x32x16_bf16 v[34:49], v[82:85], v[98:101], v[34:49]
	v_mfma_f32_32x32x16_bf16 v[66:81], v[86:89], v[102:105], v[66:81]
	ds_read_b128 v[82:85], v130 offset:27712
	ds_read_b128 v[86:89], v130 offset:27744
	s_waitcnt lgkmcnt(2)
	v_mfma_f32_32x32x16_bf16 v[34:49], v[90:93], v[102:105], v[34:49]
	s_waitcnt lgkmcnt(1)
	v_mfma_f32_32x32x16_bf16 v[66:81], v[82:85], v[106:109], v[66:81]
	ds_read_b128 v[82:85], v130 offset:32320
	ds_read_b128 v[90:93], v130 offset:32352
	s_waitcnt lgkmcnt(1)
	v_mfma_f32_32x32x16_bf16 v[34:49], v[82:85], v[106:109], v[34:49]
	v_add_f32_e32 v82, v144, v94
	v_mfma_f32_32x32x16_bf16 v[66:81], v[86:89], v[110:113], v[66:81]
	s_waitcnt lgkmcnt(0)
	v_mfma_f32_32x32x16_bf16 v[34:49], v[90:93], v[110:113], v[34:49]
	s_nop 15
	s_nop 7
	s_nop 0
	v_max3_f32 v83, v66, v67, v34
	v_max3_f32 v84, v68, v69, v35
	v_max3_f32 v83, v83, v36, v37
	v_max3_f32 v84, v84, v72, v73
	v_max3_f32 v83, v83, v70, v71
	v_max3_f32 v84, v84, v40, v41
	v_max3_f32 v83, v83, v38, v39
	v_max3_f32 v84, v84, v76, v77
	v_max3_f32 v83, v83, v74, v75
	v_max3_f32 v84, v84, v44, v45
	v_max3_f32 v83, v83, v42, v43
	v_max3_f32 v84, v84, v80, v81
	v_max3_f32 v83, v83, v78, v79
	v_max3_f32 v84, v84, v48, v49
	v_max3_f32 v83, v83, v46, v47
	v_max_f32_e32 v84, v84, v84
	v_max_f32_e32 v83, v83, v83
	v_max_f32_e32 v83, v83, v84
	v_cmp_lt_f32_e32 vcc, s47, v83
	s_cbranch_vccz .LBB0_601
; template <int DQK, int DV, bool BIAS> ...
;     ...
;         if (__any(mx > 8.f)) {
;             mx = fmaxf(mx, __shfl_xor(mx, 32));
;             const float dl = fmaxf(mx, 0.f); mhat += dl;
;             const float f = __builtin_amdgcn_exp2f(-dl);
; #pragma unroll
;             for (int r = 0; r < 16; ++r) { p0[r] -= dl; p1[r] -= dl; negm[r] = -mhat; }
;             l *= f;
; #pragma unroll
;             for (int d = 0; d < NDT; ++d)
; #pragma unroll
;                 for (int r = 0; r < 16; ++r) o[d][r] *= f;
;         }
	ds_bpermute_b32 v50, v168, v83
	s_waitcnt lgkmcnt(0)
	v_max3_f32 v52, v83, v50, 0
	v_exp_f32_e64 v54, -v52
	v_add_f32_e32 v143, v143, v52
	v_xor_b32_e32 v50, 0x80000000, v143
	v_pk_add_f32 v[66:67], v[66:67], v[52:53] op_sel_hi:[1,0] neg_lo:[0,1] neg_hi:[0,1]
	v_pk_add_f32 v[34:35], v[34:35], v[52:53] op_sel_hi:[1,0] neg_lo:[0,1] neg_hi:[0,1]
	v_pk_add_f32 v[68:69], v[68:69], v[52:53] op_sel_hi:[1,0] neg_lo:[0,1] neg_hi:[0,1]
	v_pk_add_f32 v[36:37], v[36:37], v[52:53] op_sel_hi:[1,0] neg_lo:[0,1] neg_hi:[0,1]
	v_pk_add_f32 v[70:71], v[70:71], v[52:53] op_sel_hi:[1,0] neg_lo:[0,1] neg_hi:[0,1]
	v_pk_add_f32 v[38:39], v[38:39], v[52:53] op_sel_hi:[1,0] neg_lo:[0,1] neg_hi:[0,1]
	v_pk_add_f32 v[72:73], v[72:73], v[52:53] op_sel_hi:[1,0] neg_lo:[0,1] neg_hi:[0,1]
	v_pk_add_f32 v[40:41], v[40:41], v[52:53] op_sel_hi:[1,0] neg_lo:[0,1] neg_hi:[0,1]
	v_pk_add_f32 v[74:75], v[74:75], v[52:53] op_sel_hi:[1,0] neg_lo:[0,1] neg_hi:[0,1]
	v_pk_add_f32 v[42:43], v[42:43], v[52:53] op_sel_hi:[1,0] neg_lo:[0,1] neg_hi:[0,1]
	v_pk_add_f32 v[76:77], v[76:77], v[52:53] op_sel_hi:[1,0] neg_lo:[0,1] neg_hi:[0,1]
	v_pk_add_f32 v[44:45], v[44:45], v[52:53] op_sel_hi:[1,0] neg_lo:[0,1] neg_hi:[0,1]
	v_pk_add_f32 v[78:79], v[78:79], v[52:53] op_sel_hi:[1,0] neg_lo:[0,1] neg_hi:[0,1]
	v_pk_add_f32 v[46:47], v[46:47], v[52:53] op_sel_hi:[1,0] neg_lo:[0,1] neg_hi:[0,1]
	v_pk_add_f32 v[80:81], v[80:81], v[52:53] op_sel_hi:[1,0] neg_lo:[0,1] neg_hi:[0,1]
	v_pk_add_f32 v[48:49], v[48:49], v[52:53] op_sel_hi:[1,0] neg_lo:[0,1] neg_hi:[0,1]
	v_pk_mul_f32 v[16:17], v[16:17], v[54:55] op_sel_hi:[1,0]
	v_pk_mul_f32 v[14:15], v[14:15], v[54:55] op_sel_hi:[1,0]
	v_pk_mul_f32 v[12:13], v[12:13], v[54:55] op_sel_hi:[1,0]
	v_pk_mul_f32 v[10:11], v[10:11], v[54:55] op_sel_hi:[1,0]
	v_pk_mul_f32 v[8:9], v[8:9], v[54:55] op_sel_hi:[1,0]
	v_pk_mul_f32 v[6:7], v[6:7], v[54:55] op_sel_hi:[1,0]
	v_pk_mul_f32 v[4:5], v[4:5], v[54:55] op_sel_hi:[1,0]
	v_pk_mul_f32 v[2:3], v[2:3], v[54:55] op_sel_hi:[1,0]
	v_pk_mul_f32 v[32:33], v[32:33], v[54:55] op_sel_hi:[1,0]
	v_pk_mul_f32 v[30:31], v[30:31], v[54:55] op_sel_hi:[1,0]
	v_pk_mul_f32 v[28:29], v[28:29], v[54:55] op_sel_hi:[1,0]
	v_pk_mul_f32 v[26:27], v[26:27], v[54:55] op_sel_hi:[1,0]
	v_pk_mul_f32 v[24:25], v[24:25], v[54:55] op_sel_hi:[1,0]
	v_pk_mul_f32 v[22:23], v[22:23], v[54:55] op_sel_hi:[1,0]
	v_pk_mul_f32 v[20:21], v[20:21], v[54:55] op_sel_hi:[1,0]
	v_pk_mul_f32 v[18:19], v[18:19], v[54:55] op_sel_hi:[1,0]
	v_mul_f32_e32 v82, v82, v54
	v_mov_b32_e32 v51, v50
	v_mov_b32_e32 v52, v50
	v_mov_b32_e32 v53, v50
	v_mov_b32_e32 v54, v50
	v_mov_b32_e32 v55, v50
	v_mov_b32_e32 v56, v50
	v_mov_b32_e32 v57, v50
	v_mov_b32_e32 v58, v50
	v_mov_b32_e32 v59, v50
	v_mov_b32_e32 v60, v50
	v_mov_b32_e32 v61, v50
	v_mov_b32_e32 v62, v50
	v_mov_b32_e32 v63, v50
	v_mov_b32_e32 v64, v50
	v_mov_b32_e32 v65, v50
	s_branch .LBB0_601

; #define LAS __attribute__((address_space(3)))
; __device__ __forceinline__ float max3f(float a, float b, float c) { float r; asm("v_max3_f32 %0, %1, %2, %3" : "=v"(r) : "v"(a), "v"(b), "v"(c)); return r; }
; template <int DQK, int DV, bool BIAS> ...
;     ...
;         const LAS unsigned char* kb = lds + buf * KBUF + r32 * KP + hi * 16;
; #pragma unroll
;         for (int ks = 0; ks < NKS; ++ks) {
;             const bf16x8 k0 = *(const LAS bf16x8*)(kb + ks * 32), k1 = *(const LAS bf16x8*)(kb + 32 * KP + ks * 32);
;             if (ks == 0) { p0 = __builtin_amdgcn_mfma_f32_32x32x16_bf16(k0, qf[0], negm, 0, 0, 0); p1 = __builtin_amdgcn_mfma_f32_32x32x16_bf16(k1, qf[0], negm, 0, 0, 0); }
;             else { p0 = __builtin_amdgcn_mfma_f32_32x32x16_bf16(k0, qf[ks], p0, 0, 0, 0); p1 = __builtin_amdgcn_mfma_f32_32x32x16_bf16(k1, qf[ks], p1, 0, 0, 0); }
;         }
;         if (BIAS) {
;             asm volatile("s_nop 15\n\ts_nop 7" : "+v"(p0), "+v"(p1));
;             const float d0 = qp - (float)(t * 64 + 4 * hi);
; #pragma unroll
;             for (int r = 0; r < 16; ++r) { const float dk = d0 - (float)((r & 3) + 8 * (r >> 2)); p0[r] = p0[r] - sl2 * fabsf(dk); p1[r] = p1[r] - sl2 * fabsf(dk - 32.f); }
;         } else {
;             asm volatile("s_nop 15\n\ts_nop 7" : "+v"(p0), "+v"(p1));
;         }
;         float mxa = max3f(p0[0], p0[1], p1[0]), mxb = max3f(p0[2], p0[3], p1[1]); mxa = max3f(mxa, p1[2], p1[3]);
; #pragma unroll
;         for (int r = 4; r < 16; r += 4) { mxa = max3f(mxa, p0[r], p0[r + 1]); mxb = max3f(mxb, p0[r + 2], p0[r + 3]); mxa = max3f(mxa, p1[r], p1[r + 1]); mxb = max3f(mxb, p1[r + 2], p1[r + 3]); }
;         float mx = fmaxf(mxa, mxb);
;         if (__any(mx > 8.f)) {
;             mx = fmaxf(mx, __shfl_xor(mx, 32));
;             const float dl = fmaxf(mx, 0.f); mhat += dl;
;             const float f = __builtin_amdgcn_exp2f(-dl);
; #pragma unroll
;             for (int r = 0; r < 16; ++r) { p0[r] -= dl; p1[r] -= dl; negm[r] = -mhat; }
;             l *= f;
; #pragma unroll
;             for (int d = 0; d < NDT; ++d)
; #pragma unroll
;                 for (int r = 0; r < 16; ++r) o[d][r] *= f;
;         }
.LBB0_642:
	ds_read_b128 v[34:37], v148
	ds_read_b128 v[38:41], v148 offset:32
	s_waitcnt lgkmcnt(1)
	v_mfma_f32_32x32x16_bf16 v[82:97], v[34:37], v[98:101], v[50:65]
	ds_read_b128 v[34:37], v148 offset:6656
	ds_read_b128 v[42:45], v148 offset:6688
	s_waitcnt lgkmcnt(1)
	v_mfma_f32_32x32x16_bf16 v[66:81], v[34:37], v[98:101], v[50:65]
	v_mfma_f32_32x32x16_bf16 v[82:97], v[38:41], v[102:105], v[82:97]
	ds_read_b128 v[34:37], v148 offset:64
	ds_read_b128 v[38:41], v148 offset:96
	s_waitcnt lgkmcnt(2)
	v_mfma_f32_32x32x16_bf16 v[66:81], v[42:45], v[102:105], v[66:81]
	s_waitcnt lgkmcnt(1)
	v_mfma_f32_32x32x16_bf16 v[82:97], v[34:37], v[106:109], v[82:97]
	ds_read_b128 v[34:37], v148 offset:6720
	ds_read_b128 v[42:45], v148 offset:6752
	s_waitcnt lgkmcnt(1)
	v_mfma_f32_32x32x16_bf16 v[66:81], v[34:37], v[106:109], v[66:81]
	v_mfma_f32_32x32x16_bf16 v[82:97], v[38:41], v[110:113], v[82:97]
	ds_read_b128 v[34:37], v148 offset:128
	ds_read_b128 v[38:41], v148 offset:160
	s_waitcnt lgkmcnt(2)
	v_mfma_f32_32x32x16_bf16 v[66:81], v[42:45], v[110:113], v[66:81]
	s_waitcnt lgkmcnt(1)
	v_mfma_f32_32x32x16_bf16 v[82:97], v[34:37], v[114:117], v[82:97]
	ds_read_b128 v[34:37], v148 offset:6784
	ds_read_b128 v[42:45], v148 offset:6816
	s_waitcnt lgkmcnt(1)
	v_mfma_f32_32x32x16_bf16 v[66:81], v[34:37], v[114:117], v[66:81]
	v_mfma_f32_32x32x16_bf16 v[82:97], v[38:41], v[118:121], v[82:97]
	s_waitcnt lgkmcnt(0)
	v_mfma_f32_32x32x16_bf16 v[66:81], v[42:45], v[118:121], v[66:81]
	s_nop 15
	s_nop 7
	s_nop 0
	v_max3_f32 v34, v82, v83, v66
	v_max3_f32 v35, v84, v85, v67
	v_max3_f32 v34, v34, v68, v69
	v_max3_f32 v35, v35, v88, v89
	v_max3_f32 v34, v34, v86, v87
	v_max3_f32 v35, v35, v72, v73
	v_max3_f32 v34, v34, v70, v71
	v_max3_f32 v35, v35, v92, v93
	v_max3_f32 v34, v34, v90, v91
	v_max3_f32 v35, v35, v76, v77
	v_max3_f32 v34, v34, v74, v75
	v_max3_f32 v35, v35, v96, v97
	v_max3_f32 v34, v34, v94, v95
	v_max3_f32 v35, v35, v80, v81
	v_max3_f32 v34, v34, v78, v79
	v_max_f32_e32 v35, v35, v35
	v_max_f32_e32 v34, v34, v34
	v_max_f32_e32 v34, v34, v35
	v_cmp_lt_f32_e32 vcc, s59, v34
	s_cbranch_vccz .LBB0_644
	ds_bpermute_b32 v35, v168, v34
	s_waitcnt lgkmcnt(0)
	v_max3_f32 v36, v34, v35, 0
	v_exp_f32_e64 v38, -v36
	v_add_f32_e32 v153, v153, v36
	v_xor_b32_e32 v34, 0x80000000, v153
	v_pk_add_f32 v[82:83], v[82:83], v[36:37] op_sel_hi:[1,0] neg_lo:[0,1] neg_hi:[0,1]
	v_pk_add_f32 v[66:67], v[66:67], v[36:37] op_sel_hi:[1,0] neg_lo:[0,1] neg_hi:[0,1]
	v_pk_add_f32 v[84:85], v[84:85], v[36:37] op_sel_hi:[1,0] neg_lo:[0,1] neg_hi:[0,1]
	v_pk_add_f32 v[68:69], v[68:69], v[36:37] op_sel_hi:[1,0] neg_lo:[0,1] neg_hi:[0,1]
	v_pk_add_f32 v[86:87], v[86:87], v[36:37] op_sel_hi:[1,0] neg_lo:[0,1] neg_hi:[0,1]
	v_pk_add_f32 v[70:71], v[70:71], v[36:37] op_sel_hi:[1,0] neg_lo:[0,1] neg_hi:[0,1]
	v_pk_add_f32 v[88:89], v[88:89], v[36:37] op_sel_hi:[1,0] neg_lo:[0,1] neg_hi:[0,1]
	v_pk_add_f32 v[72:73], v[72:73], v[36:37] op_sel_hi:[1,0] neg_lo:[0,1] neg_hi:[0,1]
	v_pk_add_f32 v[90:91], v[90:91], v[36:37] op_sel_hi:[1,0] neg_lo:[0,1] neg_hi:[0,1]
	v_pk_add_f32 v[74:75], v[74:75], v[36:37] op_sel_hi:[1,0] neg_lo:[0,1] neg_hi:[0,1]
	v_pk_add_f32 v[92:93], v[92:93], v[36:37] op_sel_hi:[1,0] neg_lo:[0,1] neg_hi:[0,1]
	v_pk_add_f32 v[76:77], v[76:77], v[36:37] op_sel_hi:[1,0] neg_lo:[0,1] neg_hi:[0,1]
	v_pk_add_f32 v[94:95], v[94:95], v[36:37] op_sel_hi:[1,0] neg_lo:[0,1] neg_hi:[0,1]
	v_pk_add_f32 v[78:79], v[78:79], v[36:37] op_sel_hi:[1,0] neg_lo:[0,1] neg_hi:[0,1]
	v_pk_add_f32 v[96:97], v[96:97], v[36:37] op_sel_hi:[1,0] neg_lo:[0,1] neg_hi:[0,1]
	v_pk_add_f32 v[80:81], v[80:81], v[36:37] op_sel_hi:[1,0] neg_lo:[0,1] neg_hi:[0,1]
	v_pk_mul_f32 v[32:33], v[32:33], v[38:39] op_sel_hi:[1,0]
	v_pk_mul_f32 v[30:31], v[30:31], v[38:39] op_sel_hi:[1,0]
	v_pk_mul_f32 v[28:29], v[28:29], v[38:39] op_sel_hi:[1,0]
	v_pk_mul_f32 v[26:27], v[26:27], v[38:39] op_sel_hi:[1,0]
	v_pk_mul_f32 v[24:25], v[24:25], v[38:39] op_sel_hi:[1,0]
	v_pk_mul_f32 v[22:23], v[22:23], v[38:39] op_sel_hi:[1,0]
	v_pk_mul_f32 v[20:21], v[20:21], v[38:39] op_sel_hi:[1,0]
	v_pk_mul_f32 v[18:19], v[18:19], v[38:39] op_sel_hi:[1,0]
	v_pk_mul_f32 v[16:17], v[16:17], v[38:39] op_sel_hi:[1,0]
	v_pk_mul_f32 v[14:15], v[14:15], v[38:39] op_sel_hi:[1,0]
	v_pk_mul_f32 v[12:13], v[12:13], v[38:39] op_sel_hi:[1,0]
	v_pk_mul_f32 v[10:11], v[10:11], v[38:39] op_sel_hi:[1,0]
	v_pk_mul_f32 v[8:9], v[8:9], v[38:39] op_sel_hi:[1,0]
	v_pk_mul_f32 v[6:7], v[6:7], v[38:39] op_sel_hi:[1,0]
	v_pk_mul_f32 v[4:5], v[4:5], v[38:39] op_sel_hi:[1,0]
	v_pk_mul_f32 v[2:3], v[2:3], v[38:39] op_sel_hi:[1,0]
	v_mul_f32_e32 v164, v164, v38
	v_mov_b32_e32 v35, v34
	v_mov_b32_e32 v36, v34
	v_mov_b32_e32 v37, v34
	v_mov_b32_e32 v38, v34
	v_mov_b32_e32 v39, v34
	v_mov_b32_e32 v40, v34
	v_mov_b32_e32 v41, v34
	v_mov_b32_e32 v42, v34
	v_mov_b32_e32 v43, v34
	v_mov_b32_e32 v44, v34
	v_mov_b32_e32 v45, v34
	v_mov_b32_e32 v46, v34
	v_mov_b32_e32 v47, v34
	v_mov_b32_e32 v48, v34
	v_mov_b32_e32 v49, v34
	v_mov_b32_e32 v50, v34
	v_mov_b32_e32 v51, v34
	v_mov_b32_e32 v52, v34
	v_mov_b32_e32 v53, v34
	v_mov_b32_e32 v54, v34
	v_mov_b32_e32 v55, v34
	v_mov_b32_e32 v56, v34
	v_mov_b32_e32 v57, v34
	v_mov_b32_e32 v58, v34
	v_mov_b32_e32 v59, v34
	v_mov_b32_e32 v60, v34
	v_mov_b32_e32 v61, v34
	v_mov_b32_e32 v62, v34
	v_mov_b32_e32 v63, v34
	v_mov_b32_e32 v64, v34
	v_mov_b32_e32 v65, v34
	s_branch .LBB0_645

; #define LAS __attribute__((address_space(3)))
; template <int DQK, int DV, bool BIAS> ...
;     ...
;         const LAS unsigned char* kb = lds + buf * KBUF + r32 * KP + hi * 16;
; #pragma unroll
;         for (int ks = 0; ks < NKS; ++ks) {
;             const bf16x8 k0 = *(const LAS bf16x8*)(kb + ks * 32), k1 = *(const LAS bf16x8*)(kb + 32 * KP + ks * 32);
;             if (ks == 0) { p0 = __builtin_amdgcn_mfma_f32_32x32x16_bf16(k0, qf[0], negm, 0, 0, 0); p1 = __builtin_amdgcn_mfma_f32_32x32x16_bf16(k1, qf[0], negm, 0, 0, 0); }
;             else { p0 = __builtin_amdgcn_mfma_f32_32x32x16_bf16(k0, qf[ks], p0, 0, 0, 0); p1 = __builtin_amdgcn_mfma_f32_32x32x16_bf16(k1, qf[ks], p1, 0, 0, 0); }
;         }
;         if (BIAS) {
;             asm volatile("s_nop 15\n\ts_nop 7" : "+v"(p0), "+v"(p1));
;             const float d0 = qp - (float)(t * 64 + 4 * hi);
; #pragma unroll
;             for (int r = 0; r < 16; ++r) { const float dk = d0 - (float)((r & 3) + 8 * (r >> 2)); p0[r] = p0[r] - sl2 * fabsf(dk); p1[r] = p1[r] - sl2 * fabsf(dk - 32.f); }
;         } else {
;             asm volatile("s_nop 15\n\ts_nop 7" : "+v"(p0), "+v"(p1));
;         }
;     ...
;             const LAS unsigned char* vbase = lds + VOFF + vcur * VBUF + (4 * hi + ((lane & 15) >> 2)) * 64 + ((lane >> 4) & 1) * 32 + (lane & 3) * 8;
;             float ls = 0.f;
; #pragma unroll
;             for (int hs = 0; hs < 4; ++hs) {
;                 float e[8];
; #pragma unroll
;                 for (int j = 0; j < 8; ++j) { e[j] = __builtin_amdgcn_exp2f(hs < 2 ? p0[8 * (hs & 1) + j] : p1[8 * (hs & 1) + j]); ls += e[j]; }
;                 pw[hs].x = cvtpk(e[0], e[1]); pw[hs].y = cvtpk(e[2], e[3]); pw[hs].z = cvtpk(e[4], e[5]); pw[hs].w = cvtpk(e[6], e[7]);
;                 const bf16x8 pbv = __builtin_bit_cast(bf16x8, pw[hs]);
; #pragma unroll
;                 for (int d = 0; d < NDT; ++d) { const LAS unsigned char* vp = vbase + d * 4096 + hs * 1024;
;                     const v4i16_t a0 = __builtin_amdgcn_ds_read_tr16_b64_v4i16((LAS v4i16_t*)vp), a1 = __builtin_amdgcn_ds_read_tr16_b64_v4i16((LAS v4i16_t*)(vp + 512));
;                     const bf16x8 av = {a0[0], a0[1], a0[2], a0[3], a1[0], a1[1], a1[2], a1[3]};
;                     o[d] = __builtin_amdgcn_mfma_f32_32x32x16_bf16(av, pbv, o[d], 0, 0, 0); }
;                 __builtin_amdgcn_sched_barrier(0);
;             }
;             l += ls;
.LBB0_645:
	v_exp_f32_e32 v165, v82
	v_exp_f32_e32 v166, v83
	v_exp_f32_e32 v167, v84
	v_exp_f32_e32 v169, v85
	v_exp_f32_e32 v174, v86
	v_exp_f32_e32 v175, v87
	ds_read_b64_tr_b16 v[82:83], v161 offset:53248
	ds_read_b64_tr_b16 v[84:85], v161 offset:53760
	v_exp_f32_e32 v176, v88
	v_exp_f32_e32 v177, v89
	ds_read_b64_tr_b16 v[170:171], v161 offset:57344
	ds_read_b64_tr_b16 v[172:173], v161 offset:57856
	v_cvt_pk_bf16_f32 v86, v165, v166
	v_cvt_pk_bf16_f32 v87, v167, v169
	v_cvt_pk_bf16_f32 v88, v174, v175
	v_cvt_pk_bf16_f32 v89, v176, v177
	s_waitcnt lgkmcnt(2)
	s_nop 0
	v_mfma_f32_32x32x16_bf16 v[18:33], v[82:85], v[86:89], v[18:33]
	v_add_f32_e32 v82, 0, v165
	v_add_f32_e32 v82, v166, v82
	v_add_f32_e32 v82, v167, v82
	v_add_f32_e32 v82, v169, v82
	v_add_f32_e32 v82, v174, v82
	v_add_f32_e32 v82, v175, v82
	v_add_f32_e32 v82, v176, v82
	s_waitcnt lgkmcnt(0)
	v_mfma_f32_32x32x16_bf16 v[2:17], v[170:173], v[86:89], v[2:17]
	v_add_f32_e32 v165, v177, v82
	v_exp_f32_e32 v166, v90
	v_exp_f32_e32 v167, v91
	v_exp_f32_e32 v169, v92
	v_exp_f32_e32 v170, v93
	v_exp_f32_e32 v94, v94
	v_exp_f32_e32 v95, v95
	ds_read_b64_tr_b16 v[82:83], v161 offset:54272
	ds_read_b64_tr_b16 v[84:85], v161 offset:54784
	v_exp_f32_e32 v96, v96
	v_exp_f32_e32 v97, v97
	ds_read_b64_tr_b16 v[90:91], v161 offset:58368
	ds_read_b64_tr_b16 v[92:93], v161 offset:58880
	v_cvt_pk_bf16_f32 v86, v166, v167
	v_cvt_pk_bf16_f32 v87, v169, v170
	v_cvt_pk_bf16_f32 v88, v94, v95
	v_cvt_pk_bf16_f32 v89, v96, v97
	s_waitcnt lgkmcnt(2)
	s_nop 0
	v_mfma_f32_32x32x16_bf16 v[18:33], v[82:85], v[86:89], v[18:33]
	v_add_f32_e32 v82, v166, v165
	v_add_f32_e32 v82, v167, v82
	v_add_f32_e32 v82, v169, v82
	v_add_f32_e32 v82, v170, v82
	v_add_f32_e32 v82, v94, v82
	v_add_f32_e32 v82, v95, v82
	v_add_f32_e32 v82, v96, v82
	s_waitcnt lgkmcnt(0)
	v_mfma_f32_32x32x16_bf16 v[2:17], v[90:93], v[86:89], v[2:17]
	v_add_f32_e32 v86, v97, v82
	v_exp_f32_e32 v87, v66
	v_exp_f32_e32 v88, v67
	v_exp_f32_e32 v89, v68
	v_exp_f32_e32 v90, v69
	v_exp_f32_e32 v91, v70
	v_exp_f32_e32 v92, v71
	ds_read_b64_tr_b16 v[66:67], v161 offset:55296
	ds_read_b64_tr_b16 v[68:69], v161 offset:55808
	v_exp_f32_e32 v93, v72
	v_exp_f32_e32 v94, v73
	ds_read_b64_tr_b16 v[82:83], v161 offset:59392
	ds_read_b64_tr_b16 v[84:85], v161 offset:59904
	v_cvt_pk_bf16_f32 v70, v87, v88
	v_cvt_pk_bf16_f32 v71, v89, v90
	v_cvt_pk_bf16_f32 v72, v91, v92
	v_cvt_pk_bf16_f32 v73, v93, v94
	s_waitcnt lgkmcnt(2)
	s_nop 0
	v_mfma_f32_32x32x16_bf16 v[18:33], v[66:69], v[70:73], v[18:33]
	v_add_f32_e32 v66, v87, v86
	v_add_f32_e32 v66, v88, v66
	v_add_f32_e32 v66, v89, v66
	v_add_f32_e32 v66, v90, v66
	v_add_f32_e32 v66, v91, v66
	v_add_f32_e32 v66, v92, v66
	v_add_f32_e32 v66, v93, v66
	s_waitcnt lgkmcnt(0)
	v_mfma_f32_32x32x16_bf16 v[2:17], v[82:85], v[70:73], v[2:17]
	v_add_f32_e32 v82, v94, v66
	v_exp_f32_e32 v83, v74
	v_exp_f32_e32 v84, v75
	v_exp_f32_e32 v85, v76
	v_exp_f32_e32 v86, v77
	v_exp_f32_e32 v78, v78
	v_exp_f32_e32 v79, v79
	ds_read_b64_tr_b16 v[66:67], v161 offset:56320
	ds_read_b64_tr_b16 v[68:69], v161 offset:56832
	v_exp_f32_e32 v80, v80
	v_exp_f32_e32 v81, v81
	ds_read_b64_tr_b16 v[74:75], v161 offset:60416
	ds_read_b64_tr_b16 v[76:77], v161 offset:60928
	v_cvt_pk_bf16_f32 v70, v83, v84
	v_cvt_pk_bf16_f32 v71, v85, v86
	v_cvt_pk_bf16_f32 v72, v78, v79
	v_cvt_pk_bf16_f32 v73, v80, v81
	s_waitcnt lgkmcnt(2)
	s_nop 0
	v_mfma_f32_32x32x16_bf16 v[18:33], v[66:69], v[70:73], v[18:33]
	v_add_f32_e32 v66, v83, v82
	v_add_f32_e32 v66, v84, v66
	v_add_f32_e32 v66, v85, v66
	v_add_f32_e32 v66, v86, v66
	v_add_f32_e32 v66, v78, v66
	v_add_f32_e32 v66, v79, v66
	v_add_f32_e32 v66, v80, v66
	s_waitcnt lgkmcnt(0)
	v_mfma_f32_32x32x16_bf16 v[2:17], v[74:77], v[70:73], v[2:17]
	v_add_f32_e32 v165, v81, v66
	ds_read_b128 v[66:69], v148 offset:13312
	ds_read_b128 v[170:173], v148 offset:13344
	ds_read_b128 v[174:177], v148 offset:19968
	ds_read_b128 v[178:181], v148 offset:20000
	v_add_f32_e32 v164, v164, v165
	s_waitcnt lgkmcnt(3)
	v_mfma_f32_32x32x16_bf16 v[82:97], v[66:69], v[98:101], v[34:49]
	s_waitcnt lgkmcnt(1)
	v_mfma_f32_32x32x16_bf16 v[66:81], v[174:177], v[98:101], v[34:49]
	v_mfma_f32_32x32x16_bf16 v[82:97], v[170:173], v[102:105], v[82:97]
	ds_read_b128 v[170:173], v148 offset:13376
	ds_read_b128 v[174:177], v148 offset:13408
	s_waitcnt lgkmcnt(2)
	v_mfma_f32_32x32x16_bf16 v[66:81], v[178:181], v[102:105], v[66:81]
	s_waitcnt lgkmcnt(1)
	v_mfma_f32_32x32x16_bf16 v[82:97], v[170:173], v[106:109], v[82:97]
	ds_read_b128 v[170:173], v148 offset:20032
	ds_read_b128 v[178:181], v148 offset:20064
	s_waitcnt lgkmcnt(1)
	v_mfma_f32_32x32x16_bf16 v[66:81], v[170:173], v[106:109], v[66:81]
	v_mfma_f32_32x32x16_bf16 v[82:97], v[174:177], v[110:113], v[82:97]
	ds_read_b128 v[170:173], v148 offset:13440
	ds_read_b128 v[174:177], v148 offset:13472
	s_waitcnt lgkmcnt(2)
	v_mfma_f32_32x32x16_bf16 v[66:81], v[178:181], v[110:113], v[66:81]
	s_waitcnt lgkmcnt(1)
	v_mfma_f32_32x32x16_bf16 v[82:97], v[170:173], v[114:117], v[82:97]
	ds_read_b128 v[170:173], v148 offset:20096
	ds_read_b128 v[178:181], v148 offset:20128
	s_waitcnt lgkmcnt(1)
	v_mfma_f32_32x32x16_bf16 v[66:81], v[170:173], v[114:117], v[66:81]
	v_mfma_f32_32x32x16_bf16 v[82:97], v[174:177], v[118:121], v[82:97]
	s_waitcnt lgkmcnt(0)
	v_mfma_f32_32x32x16_bf16 v[66:81], v[178:181], v[118:121], v[66:81]
	s_nop 15
	s_nop 7
	s_nop 0
	v_max3_f32 v165, v82, v83, v66
	v_max3_f32 v166, v84, v85, v67
	v_max3_f32 v165, v165, v68, v69
	v_max3_f32 v166, v166, v88, v89
	v_max3_f32 v165, v165, v86, v87
	v_max3_f32 v166, v166, v72, v73
	v_max3_f32 v165, v165, v70, v71
	v_max3_f32 v166, v166, v92, v93
	v_max3_f32 v165, v165, v90, v91
	v_max3_f32 v166, v166, v76, v77
	v_max3_f32 v165, v165, v74, v75
	v_max3_f32 v166, v166, v96, v97
	v_max3_f32 v165, v165, v94, v95
	v_max3_f32 v166, v166, v80, v81
	v_max3_f32 v165, v165, v78, v79
	v_max_f32_e32 v166, v166, v166
	v_max_f32_e32 v165, v165, v165
	v_max_f32_e32 v165, v165, v166
	v_cmp_lt_f32_e32 vcc, s59, v165
	s_cbranch_vccz .LBB0_647
; template <int DQK, int DV, bool BIAS> ...
;     ...
;         if (__any(mx > 8.f)) {
;             mx = fmaxf(mx, __shfl_xor(mx, 32));
;             const float dl = fmaxf(mx, 0.f); mhat += dl;
;             const float f = __builtin_amdgcn_exp2f(-dl);
; #pragma unroll
;             for (int r = 0; r < 16; ++r) { p0[r] -= dl; p1[r] -= dl; negm[r] = -mhat; }
;             l *= f;
; #pragma unroll
;             for (int d = 0; d < NDT; ++d)
; #pragma unroll
;                 for (int r = 0; r < 16; ++r) o[d][r] *= f;
;         }
	ds_bpermute_b32 v34, v168, v165
	s_waitcnt lgkmcnt(0)
	v_max3_f32 v36, v165, v34, 0
	v_exp_f32_e64 v38, -v36
	v_add_f32_e32 v153, v153, v36
	v_xor_b32_e32 v34, 0x80000000, v153
	v_pk_add_f32 v[82:83], v[82:83], v[36:37] op_sel_hi:[1,0] neg_lo:[0,1] neg_hi:[0,1]
	v_pk_add_f32 v[66:67], v[66:67], v[36:37] op_sel_hi:[1,0] neg_lo:[0,1] neg_hi:[0,1]
	v_pk_add_f32 v[84:85], v[84:85], v[36:37] op_sel_hi:[1,0] neg_lo:[0,1] neg_hi:[0,1]
	v_pk_add_f32 v[68:69], v[68:69], v[36:37] op_sel_hi:[1,0] neg_lo:[0,1] neg_hi:[0,1]
	v_pk_add_f32 v[86:87], v[86:87], v[36:37] op_sel_hi:[1,0] neg_lo:[0,1] neg_hi:[0,1]
	v_pk_add_f32 v[70:71], v[70:71], v[36:37] op_sel_hi:[1,0] neg_lo:[0,1] neg_hi:[0,1]
	v_pk_add_f32 v[88:89], v[88:89], v[36:37] op_sel_hi:[1,0] neg_lo:[0,1] neg_hi:[0,1]
	v_pk_add_f32 v[72:73], v[72:73], v[36:37] op_sel_hi:[1,0] neg_lo:[0,1] neg_hi:[0,1]
	v_pk_add_f32 v[90:91], v[90:91], v[36:37] op_sel_hi:[1,0] neg_lo:[0,1] neg_hi:[0,1]
	v_pk_add_f32 v[74:75], v[74:75], v[36:37] op_sel_hi:[1,0] neg_lo:[0,1] neg_hi:[0,1]
	v_pk_add_f32 v[92:93], v[92:93], v[36:37] op_sel_hi:[1,0] neg_lo:[0,1] neg_hi:[0,1]
	v_pk_add_f32 v[76:77], v[76:77], v[36:37] op_sel_hi:[1,0] neg_lo:[0,1] neg_hi:[0,1]
	v_pk_add_f32 v[94:95], v[94:95], v[36:37] op_sel_hi:[1,0] neg_lo:[0,1] neg_hi:[0,1]
	v_pk_add_f32 v[78:79], v[78:79], v[36:37] op_sel_hi:[1,0] neg_lo:[0,1] neg_hi:[0,1]
	v_pk_add_f32 v[96:97], v[96:97], v[36:37] op_sel_hi:[1,0] neg_lo:[0,1] neg_hi:[0,1]
	v_pk_add_f32 v[80:81], v[80:81], v[36:37] op_sel_hi:[1,0] neg_lo:[0,1] neg_hi:[0,1]
	v_pk_mul_f32 v[32:33], v[32:33], v[38:39] op_sel_hi:[1,0]
	v_pk_mul_f32 v[30:31], v[30:31], v[38:39] op_sel_hi:[1,0]
	v_pk_mul_f32 v[28:29], v[28:29], v[38:39] op_sel_hi:[1,0]
	v_pk_mul_f32 v[26:27], v[26:27], v[38:39] op_sel_hi:[1,0]
	v_pk_mul_f32 v[24:25], v[24:25], v[38:39] op_sel_hi:[1,0]
	v_pk_mul_f32 v[22:23], v[22:23], v[38:39] op_sel_hi:[1,0]
	v_pk_mul_f32 v[20:21], v[20:21], v[38:39] op_sel_hi:[1,0]
	v_pk_mul_f32 v[18:19], v[18:19], v[38:39] op_sel_hi:[1,0]
	v_pk_mul_f32 v[16:17], v[16:17], v[38:39] op_sel_hi:[1,0]
	v_pk_mul_f32 v[14:15], v[14:15], v[38:39] op_sel_hi:[1,0]
	v_pk_mul_f32 v[12:13], v[12:13], v[38:39] op_sel_hi:[1,0]
	v_pk_mul_f32 v[10:11], v[10:11], v[38:39] op_sel_hi:[1,0]
	v_pk_mul_f32 v[8:9], v[8:9], v[38:39] op_sel_hi:[1,0]
	v_pk_mul_f32 v[6:7], v[6:7], v[38:39] op_sel_hi:[1,0]
	v_pk_mul_f32 v[4:5], v[4:5], v[38:39] op_sel_hi:[1,0]
	v_pk_mul_f32 v[2:3], v[2:3], v[38:39] op_sel_hi:[1,0]
	v_mul_f32_e32 v164, v164, v38
	v_mov_b32_e32 v35, v34
	v_mov_b32_e32 v36, v34
	v_mov_b32_e32 v37, v34
	v_mov_b32_e32 v38, v34
	v_mov_b32_e32 v39, v34
	v_mov_b32_e32 v40, v34
	v_mov_b32_e32 v41, v34
	v_mov_b32_e32 v42, v34
	v_mov_b32_e32 v43, v34
	v_mov_b32_e32 v44, v34
	v_mov_b32_e32 v45, v34
	v_mov_b32_e32 v46, v34
	v_mov_b32_e32 v47, v34
	v_mov_b32_e32 v48, v34
	v_mov_b32_e32 v49, v34
	v_mov_b32_e32 v50, v34
	v_mov_b32_e32 v51, v34
	v_mov_b32_e32 v52, v34
	v_mov_b32_e32 v53, v34
	v_mov_b32_e32 v54, v34
	v_mov_b32_e32 v55, v34
	v_mov_b32_e32 v56, v34
	v_mov_b32_e32 v57, v34
	v_mov_b32_e32 v58, v34
	v_mov_b32_e32 v59, v34
	v_mov_b32_e32 v60, v34
	v_mov_b32_e32 v61, v34
	v_mov_b32_e32 v62, v34
	v_mov_b32_e32 v63, v34
	v_mov_b32_e32 v64, v34
	v_mov_b32_e32 v65, v34

; #define LAS __attribute__((address_space(3)))
; __device__ __forceinline__ float max3f(float a, float b, float c) { float r; asm("v_max3_f32 %0, %1, %2, %3" : "=v"(r) : "v"(a), "v"(b), "v"(c)); return r; }
; template <int DQK, int DV, bool BIAS> ...
;     ...
;         const LAS unsigned char* kb = lds + buf * KBUF + r32 * KP + hi * 16;
; #pragma unroll
;         for (int ks = 0; ks < NKS; ++ks) {
;             const bf16x8 k0 = *(const LAS bf16x8*)(kb + ks * 32), k1 = *(const LAS bf16x8*)(kb + 32 * KP + ks * 32);
;             if (ks == 0) { p0 = __builtin_amdgcn_mfma_f32_32x32x16_bf16(k0, qf[0], negm, 0, 0, 0); p1 = __builtin_amdgcn_mfma_f32_32x32x16_bf16(k1, qf[0], negm, 0, 0, 0); }
;             else { p0 = __builtin_amdgcn_mfma_f32_32x32x16_bf16(k0, qf[ks], p0, 0, 0, 0); p1 = __builtin_amdgcn_mfma_f32_32x32x16_bf16(k1, qf[ks], p1, 0, 0, 0); }
;         }
;         if (BIAS) {
;             asm volatile("s_nop 15\n\ts_nop 7" : "+v"(p0), "+v"(p1));
;             const float d0 = qp - (float)(t * 64 + 4 * hi);
; #pragma unroll
;             for (int r = 0; r < 16; ++r) { const float dk = d0 - (float)((r & 3) + 8 * (r >> 2)); p0[r] = p0[r] - sl2 * fabsf(dk); p1[r] = p1[r] - sl2 * fabsf(dk - 32.f); }
;         } else {
;             asm volatile("s_nop 15\n\ts_nop 7" : "+v"(p0), "+v"(p1));
;         }
;         float mxa = max3f(p0[0], p0[1], p1[0]), mxb = max3f(p0[2], p0[3], p1[1]); mxa = max3f(mxa, p1[2], p1[3]);
; #pragma unroll
;         for (int r = 4; r < 16; r += 4) { mxa = max3f(mxa, p0[r], p0[r + 1]); mxb = max3f(mxb, p0[r + 2], p0[r + 3]); mxa = max3f(mxa, p1[r], p1[r + 1]); mxb = max3f(mxb, p1[r + 2], p1[r + 3]); }
;         float mx = fmaxf(mxa, mxb);
;         if (__any(mx > 8.f)) {
;             mx = fmaxf(mx, __shfl_xor(mx, 32));
;             const float dl = fmaxf(mx, 0.f); mhat += dl;
;             const float f = __builtin_amdgcn_exp2f(-dl);
; #pragma unroll
;             for (int r = 0; r < 16; ++r) { p0[r] -= dl; p1[r] -= dl; negm[r] = -mhat; }
;             l *= f;
; #pragma unroll
;             for (int d = 0; d < NDT; ++d)
; #pragma unroll
;                 for (int r = 0; r < 16; ++r) o[d][r] *= f;
;         }
.LBB0_658:
	ds_read_b128 v[66:69], v148 offset:26624
	ds_read_b128 v[198:201], v148 offset:26656
	ds_read_b128 v[202:205], v148 offset:33280
	ds_read_b128 v[206:209], v148 offset:33312
	v_add_f32_e32 v170, 0, v170
	v_add_f32_e32 v170, v171, v170
	s_waitcnt lgkmcnt(3)
	v_mfma_f32_32x32x16_bf16 v[82:97], v[66:69], v[98:101], v[34:49]
	v_add_f32_e32 v165, v165, v170
	v_add_f32_e32 v165, v166, v165
	v_add_f32_e32 v165, v167, v165
	v_add_f32_e32 v165, v169, v165
	v_add_f32_e32 v165, v172, v165
	v_add_f32_e32 v165, v173, v165
	v_add_f32_e32 v165, v175, v165
	s_waitcnt lgkmcnt(1)
	v_mfma_f32_32x32x16_bf16 v[66:81], v[202:205], v[98:101], v[34:49]
	v_add_f32_e32 v165, v176, v165
	v_add_f32_e32 v165, v177, v165
	v_add_f32_e32 v165, v178, v165
	v_add_f32_e32 v165, v179, v165
	v_add_f32_e32 v165, v174, v165
	v_add_f32_e32 v165, v180, v165
	v_add_f32_e32 v165, v181, v165
	v_mfma_f32_32x32x16_bf16 v[82:97], v[198:201], v[102:105], v[82:97]
	ds_read_b128 v[198:201], v148 offset:26688
	ds_read_b128 v[202:205], v148 offset:26720
	v_add_f32_e32 v165, v185, v165
	v_add_f32_e32 v165, v186, v165
	v_add_f32_e32 v165, v187, v165
	v_add_f32_e32 v165, v182, v165
	v_add_f32_e32 v165, v183, v165
	v_add_f32_e32 v165, v184, v165
	s_waitcnt lgkmcnt(2)
	v_mfma_f32_32x32x16_bf16 v[66:81], v[206:209], v[102:105], v[66:81]
	v_add_f32_e32 v165, v188, v165
	v_add_f32_e32 v165, v189, v165
	v_add_f32_e32 v165, v194, v165
	v_add_f32_e32 v165, v195, v165
	v_add_f32_e32 v165, v190, v165
	v_add_f32_e32 v165, v191, v165
	v_add_f32_e32 v165, v192, v165
	s_waitcnt lgkmcnt(1)
	v_mfma_f32_32x32x16_bf16 v[82:97], v[198:201], v[106:109], v[82:97]
	ds_read_b128 v[198:201], v148 offset:33344
	ds_read_b128 v[206:209], v148 offset:33376
	ds_read_b128 v[170:173], v148 offset:26752
	v_add_f32_e32 v165, v193, v165
	v_add_f32_e32 v165, v196, v165
	v_add_f32_e32 v165, v197, v165
	v_add_f32_e32 v164, v164, v165
	s_waitcnt lgkmcnt(2)
	v_mfma_f32_32x32x16_bf16 v[66:81], v[198:201], v[106:109], v[66:81]
	ds_read_b128 v[176:179], v148 offset:33408
	ds_read_b128 v[198:201], v148 offset:26784
	v_mfma_f32_32x32x16_bf16 v[82:97], v[202:205], v[110:113], v[82:97]
	s_waitcnt lgkmcnt(3)
	v_mfma_f32_32x32x16_bf16 v[66:81], v[206:209], v[110:113], v[66:81]
	s_waitcnt lgkmcnt(2)
	v_mfma_f32_32x32x16_bf16 v[82:97], v[170:173], v[114:117], v[82:97]
	ds_read_b128 v[170:173], v148 offset:33440
	s_waitcnt lgkmcnt(2)
	v_mfma_f32_32x32x16_bf16 v[66:81], v[176:179], v[114:117], v[66:81]
	s_waitcnt lgkmcnt(1)
	v_mfma_f32_32x32x16_bf16 v[82:97], v[198:201], v[118:121], v[82:97]
	s_waitcnt lgkmcnt(0)
	v_mfma_f32_32x32x16_bf16 v[66:81], v[170:173], v[118:121], v[66:81]
	s_nop 15
	s_nop 7
	s_nop 0
	v_max3_f32 v165, v82, v83, v66
	v_max3_f32 v166, v84, v85, v67
	v_max3_f32 v165, v165, v68, v69
	v_max3_f32 v166, v166, v88, v89
	v_max3_f32 v165, v165, v86, v87
	v_max3_f32 v166, v166, v72, v73
	v_max3_f32 v165, v165, v70, v71
	v_max3_f32 v166, v166, v92, v93
	v_max3_f32 v165, v165, v90, v91
	v_max3_f32 v166, v166, v76, v77
	v_max3_f32 v165, v165, v74, v75
	v_max3_f32 v166, v166, v96, v97
	v_max3_f32 v165, v165, v94, v95
	v_max3_f32 v166, v166, v80, v81
	v_max3_f32 v165, v165, v78, v79
	v_max_f32_e32 v166, v166, v166
	v_max_f32_e32 v165, v165, v165
	v_max_f32_e32 v165, v165, v166
	v_cmp_lt_f32_e32 vcc, s59, v165
	s_cbranch_vccz .LBB0_660
	ds_bpermute_b32 v34, v168, v165
	s_waitcnt lgkmcnt(0)
	v_max3_f32 v36, v165, v34, 0
	v_exp_f32_e64 v38, -v36
	v_add_f32_e32 v153, v153, v36
	v_xor_b32_e32 v34, 0x80000000, v153
	v_pk_add_f32 v[82:83], v[82:83], v[36:37] op_sel_hi:[1,0] neg_lo:[0,1] neg_hi:[0,1]
	v_pk_add_f32 v[66:67], v[66:67], v[36:37] op_sel_hi:[1,0] neg_lo:[0,1] neg_hi:[0,1]
	v_pk_add_f32 v[84:85], v[84:85], v[36:37] op_sel_hi:[1,0] neg_lo:[0,1] neg_hi:[0,1]
	v_pk_add_f32 v[68:69], v[68:69], v[36:37] op_sel_hi:[1,0] neg_lo:[0,1] neg_hi:[0,1]
	v_pk_add_f32 v[86:87], v[86:87], v[36:37] op_sel_hi:[1,0] neg_lo:[0,1] neg_hi:[0,1]
	v_pk_add_f32 v[70:71], v[70:71], v[36:37] op_sel_hi:[1,0] neg_lo:[0,1] neg_hi:[0,1]
	v_pk_add_f32 v[88:89], v[88:89], v[36:37] op_sel_hi:[1,0] neg_lo:[0,1] neg_hi:[0,1]
	v_pk_add_f32 v[72:73], v[72:73], v[36:37] op_sel_hi:[1,0] neg_lo:[0,1] neg_hi:[0,1]
	v_pk_add_f32 v[90:91], v[90:91], v[36:37] op_sel_hi:[1,0] neg_lo:[0,1] neg_hi:[0,1]
	v_pk_add_f32 v[74:75], v[74:75], v[36:37] op_sel_hi:[1,0] neg_lo:[0,1] neg_hi:[0,1]
	v_pk_add_f32 v[92:93], v[92:93], v[36:37] op_sel_hi:[1,0] neg_lo:[0,1] neg_hi:[0,1]
	v_pk_add_f32 v[76:77], v[76:77], v[36:37] op_sel_hi:[1,0] neg_lo:[0,1] neg_hi:[0,1]
	v_pk_add_f32 v[94:95], v[94:95], v[36:37] op_sel_hi:[1,0] neg_lo:[0,1] neg_hi:[0,1]
	v_pk_add_f32 v[78:79], v[78:79], v[36:37] op_sel_hi:[1,0] neg_lo:[0,1] neg_hi:[0,1]
	v_pk_add_f32 v[96:97], v[96:97], v[36:37] op_sel_hi:[1,0] neg_lo:[0,1] neg_hi:[0,1]
	v_pk_add_f32 v[80:81], v[80:81], v[36:37] op_sel_hi:[1,0] neg_lo:[0,1] neg_hi:[0,1]
	v_pk_mul_f32 v[32:33], v[32:33], v[38:39] op_sel_hi:[1,0]
	v_pk_mul_f32 v[30:31], v[30:31], v[38:39] op_sel_hi:[1,0]
	v_pk_mul_f32 v[28:29], v[28:29], v[38:39] op_sel_hi:[1,0]
	v_pk_mul_f32 v[26:27], v[26:27], v[38:39] op_sel_hi:[1,0]
	v_pk_mul_f32 v[24:25], v[24:25], v[38:39] op_sel_hi:[1,0]
	v_pk_mul_f32 v[22:23], v[22:23], v[38:39] op_sel_hi:[1,0]
	v_pk_mul_f32 v[20:21], v[20:21], v[38:39] op_sel_hi:[1,0]
	v_pk_mul_f32 v[18:19], v[18:19], v[38:39] op_sel_hi:[1,0]
	v_pk_mul_f32 v[16:17], v[16:17], v[38:39] op_sel_hi:[1,0]
	v_pk_mul_f32 v[14:15], v[14:15], v[38:39] op_sel_hi:[1,0]
	v_pk_mul_f32 v[12:13], v[12:13], v[38:39] op_sel_hi:[1,0]
	v_pk_mul_f32 v[10:11], v[10:11], v[38:39] op_sel_hi:[1,0]
	v_pk_mul_f32 v[8:9], v[8:9], v[38:39] op_sel_hi:[1,0]
	v_pk_mul_f32 v[6:7], v[6:7], v[38:39] op_sel_hi:[1,0]
	v_pk_mul_f32 v[4:5], v[4:5], v[38:39] op_sel_hi:[1,0]
	v_pk_mul_f32 v[2:3], v[2:3], v[38:39] op_sel_hi:[1,0]
	v_mul_f32_e32 v164, v164, v38
	v_mov_b32_e32 v35, v34
	v_mov_b32_e32 v36, v34
	v_mov_b32_e32 v37, v34
	v_mov_b32_e32 v38, v34
	v_mov_b32_e32 v39, v34
	v_mov_b32_e32 v40, v34
	v_mov_b32_e32 v41, v34
	v_mov_b32_e32 v42, v34
	v_mov_b32_e32 v43, v34
	v_mov_b32_e32 v44, v34
	v_mov_b32_e32 v45, v34
	v_mov_b32_e32 v46, v34
	v_mov_b32_e32 v47, v34
	v_mov_b32_e32 v48, v34
	v_mov_b32_e32 v49, v34
	v_mov_b32_e32 v50, v34
	v_mov_b32_e32 v51, v34
	v_mov_b32_e32 v52, v34
	v_mov_b32_e32 v53, v34
	v_mov_b32_e32 v54, v34
	v_mov_b32_e32 v55, v34
	v_mov_b32_e32 v56, v34
	v_mov_b32_e32 v57, v34
	v_mov_b32_e32 v58, v34
	v_mov_b32_e32 v59, v34
	v_mov_b32_e32 v60, v34
	v_mov_b32_e32 v61, v34
	v_mov_b32_e32 v62, v34
	v_mov_b32_e32 v63, v34
	v_mov_b32_e32 v64, v34
	v_mov_b32_e32 v65, v34
; #define LAS __attribute__((address_space(3)))
; template <int DQK, int DV, bool BIAS> ...
;     ...
;         const LAS unsigned char* kb = lds + buf * KBUF + r32 * KP + hi * 16;
; #pragma unroll
;         for (int ks = 0; ks < NKS; ++ks) {
;             const bf16x8 k0 = *(const LAS bf16x8*)(kb + ks * 32), k1 = *(const LAS bf16x8*)(kb + 32 * KP + ks * 32);
;             if (ks == 0) { p0 = __builtin_amdgcn_mfma_f32_32x32x16_bf16(k0, qf[0], negm, 0, 0, 0); p1 = __builtin_amdgcn_mfma_f32_32x32x16_bf16(k1, qf[0], negm, 0, 0, 0); }
;             else { p0 = __builtin_amdgcn_mfma_f32_32x32x16_bf16(k0, qf[ks], p0, 0, 0, 0); p1 = __builtin_amdgcn_mfma_f32_32x32x16_bf16(k1, qf[ks], p1, 0, 0, 0); }
;         }
;         if (BIAS) {
;             asm volatile("s_nop 15\n\ts_nop 7" : "+v"(p0), "+v"(p1));
;             const float d0 = qp - (float)(t * 64 + 4 * hi);
; #pragma unroll
;             for (int r = 0; r < 16; ++r) { const float dk = d0 - (float)((r & 3) + 8 * (r >> 2)); p0[r] = p0[r] - sl2 * fabsf(dk); p1[r] = p1[r] - sl2 * fabsf(dk - 32.f); }
;         } else {
;             asm volatile("s_nop 15\n\ts_nop 7" : "+v"(p0), "+v"(p1));
;         }
;     ...
;             const LAS unsigned char* vbase = lds + VOFF + vcur * VBUF + (4 * hi + ((lane & 15) >> 2)) * 64 + ((lane >> 4) & 1) * 32 + (lane & 3) * 8;
;             float ls = 0.f;
; #pragma unroll
;             for (int hs = 0; hs < 4; ++hs) {
;                 float e[8];
; #pragma unroll
;                 for (int j = 0; j < 8; ++j) { e[j] = __builtin_amdgcn_exp2f(hs < 2 ? p0[8 * (hs & 1) + j] : p1[8 * (hs & 1) + j]); ls += e[j]; }
;                 pw[hs].x = cvtpk(e[0], e[1]); pw[hs].y = cvtpk(e[2], e[3]); pw[hs].z = cvtpk(e[4], e[5]); pw[hs].w = cvtpk(e[6], e[7]);
;                 const bf16x8 pbv = __builtin_bit_cast(bf16x8, pw[hs]);
; #pragma unroll
;                 for (int d = 0; d < NDT; ++d) { const LAS unsigned char* vp = vbase + d * 4096 + hs * 1024;
;                     const v4i16_t a0 = __builtin_amdgcn_ds_read_tr16_b64_v4i16((LAS v4i16_t*)vp), a1 = __builtin_amdgcn_ds_read_tr16_b64_v4i16((LAS v4i16_t*)(vp + 512));
;                     const bf16x8 av = {a0[0], a0[1], a0[2], a0[3], a1[0], a1[1], a1[2], a1[3]};
;                     o[d] = __builtin_amdgcn_mfma_f32_32x32x16_bf16(av, pbv, o[d], 0, 0, 0); }
;                 __builtin_amdgcn_sched_barrier(0);
;             }
;             l += ls;
.LBB0_660:
	v_exp_f32_e32 v165, v82
	v_exp_f32_e32 v166, v83
	v_exp_f32_e32 v167, v84
	v_exp_f32_e32 v169, v85
	v_exp_f32_e32 v174, v86
	v_exp_f32_e32 v175, v87
	ds_read_b64_tr_b16 v[82:83], v162 offset:16384
	ds_read_b64_tr_b16 v[84:85], v162 offset:16896
	v_exp_f32_e32 v176, v88
	v_exp_f32_e32 v177, v89
	ds_read_b64_tr_b16 v[170:171], v162 offset:20480
	ds_read_b64_tr_b16 v[172:173], v162 offset:20992
	v_cvt_pk_bf16_f32 v86, v165, v166
	v_cvt_pk_bf16_f32 v87, v167, v169
	v_cvt_pk_bf16_f32 v88, v174, v175
	v_cvt_pk_bf16_f32 v89, v176, v177
	s_waitcnt lgkmcnt(2)
	s_nop 0
	v_mfma_f32_32x32x16_bf16 v[18:33], v[82:85], v[86:89], v[18:33]
	v_add_f32_e32 v82, 0, v165
	v_add_f32_e32 v82, v166, v82
	v_add_f32_e32 v82, v167, v82
	v_add_f32_e32 v82, v169, v82
	v_add_f32_e32 v82, v174, v82
	v_add_f32_e32 v82, v175, v82
	v_add_f32_e32 v82, v176, v82
	s_waitcnt lgkmcnt(0)
	v_mfma_f32_32x32x16_bf16 v[2:17], v[170:173], v[86:89], v[2:17]
	v_add_f32_e32 v165, v177, v82
	v_exp_f32_e32 v166, v90
	v_exp_f32_e32 v167, v91
	v_exp_f32_e32 v169, v92
	v_exp_f32_e32 v170, v93
	v_exp_f32_e32 v94, v94
	v_exp_f32_e32 v95, v95
	ds_read_b64_tr_b16 v[82:83], v162 offset:17408
	ds_read_b64_tr_b16 v[84:85], v162 offset:17920
	v_exp_f32_e32 v96, v96
	v_exp_f32_e32 v97, v97
	ds_read_b64_tr_b16 v[90:91], v162 offset:21504
	ds_read_b64_tr_b16 v[92:93], v162 offset:22016
	v_cvt_pk_bf16_f32 v86, v166, v167
	v_cvt_pk_bf16_f32 v87, v169, v170
	v_cvt_pk_bf16_f32 v88, v94, v95
	v_cvt_pk_bf16_f32 v89, v96, v97
	s_waitcnt lgkmcnt(2)
	s_nop 0
	v_mfma_f32_32x32x16_bf16 v[18:33], v[82:85], v[86:89], v[18:33]
	v_add_f32_e32 v82, v166, v165
	v_add_f32_e32 v82, v167, v82
	v_add_f32_e32 v82, v169, v82
	v_add_f32_e32 v82, v170, v82
	v_add_f32_e32 v82, v94, v82
	v_add_f32_e32 v82, v95, v82
	v_add_f32_e32 v82, v96, v82
	s_waitcnt lgkmcnt(0)
	v_mfma_f32_32x32x16_bf16 v[2:17], v[90:93], v[86:89], v[2:17]
	v_add_f32_e32 v86, v97, v82
	v_exp_f32_e32 v87, v66
	v_exp_f32_e32 v88, v67
	v_exp_f32_e32 v89, v68
	v_exp_f32_e32 v90, v69
	v_exp_f32_e32 v91, v70
	v_exp_f32_e32 v92, v71
	ds_read_b64_tr_b16 v[66:67], v162 offset:18432
	ds_read_b64_tr_b16 v[68:69], v162 offset:18944
	v_exp_f32_e32 v93, v72
	v_exp_f32_e32 v94, v73
	ds_read_b64_tr_b16 v[82:83], v162 offset:22528
	ds_read_b64_tr_b16 v[84:85], v162 offset:23040
	v_cvt_pk_bf16_f32 v70, v87, v88
	v_cvt_pk_bf16_f32 v71, v89, v90
	v_cvt_pk_bf16_f32 v72, v91, v92
	v_cvt_pk_bf16_f32 v73, v93, v94
	s_waitcnt lgkmcnt(2)
	s_nop 0
	v_mfma_f32_32x32x16_bf16 v[18:33], v[66:69], v[70:73], v[18:33]
	v_add_f32_e32 v66, v87, v86
	v_add_f32_e32 v66, v88, v66
	v_add_f32_e32 v66, v89, v66
	v_add_f32_e32 v66, v90, v66
	v_add_f32_e32 v66, v91, v66
	v_add_f32_e32 v66, v92, v66
	v_add_f32_e32 v66, v93, v66
	s_waitcnt lgkmcnt(0)
	v_mfma_f32_32x32x16_bf16 v[2:17], v[82:85], v[70:73], v[2:17]
	v_add_f32_e32 v82, v94, v66
	v_exp_f32_e32 v83, v74
	v_exp_f32_e32 v84, v75
	v_exp_f32_e32 v85, v76
	v_exp_f32_e32 v86, v77
	v_exp_f32_e32 v78, v78
	v_exp_f32_e32 v79, v79
	ds_read_b64_tr_b16 v[66:67], v162 offset:19456
	ds_read_b64_tr_b16 v[68:69], v162 offset:19968
	v_exp_f32_e32 v80, v80
	v_exp_f32_e32 v81, v81
	ds_read_b64_tr_b16 v[74:75], v162 offset:23552
	ds_read_b64_tr_b16 v[76:77], v162 offset:24064
	v_cvt_pk_bf16_f32 v70, v83, v84
	v_cvt_pk_bf16_f32 v71, v85, v86
	v_cvt_pk_bf16_f32 v72, v78, v79
	v_cvt_pk_bf16_f32 v73, v80, v81
	s_waitcnt lgkmcnt(2)
	s_nop 0
	v_mfma_f32_32x32x16_bf16 v[18:33], v[66:69], v[70:73], v[18:33]
	v_add_f32_e32 v66, v83, v82
	v_add_f32_e32 v66, v84, v66
	v_add_f32_e32 v66, v85, v66
	v_add_f32_e32 v66, v86, v66
	v_add_f32_e32 v66, v78, v66
	v_add_f32_e32 v66, v79, v66
	v_add_f32_e32 v66, v80, v66
	s_waitcnt lgkmcnt(0)
	v_mfma_f32_32x32x16_bf16 v[2:17], v[74:77], v[70:73], v[2:17]
	v_add_f32_e32 v94, v81, v66
	ds_read_b128 v[82:85], v148 offset:39936
	ds_read_b128 v[86:89], v148 offset:39968
	s_waitcnt lgkmcnt(1)
	v_mfma_f32_32x32x16_bf16 v[66:81], v[82:85], v[98:101], v[34:49]
	ds_read_b128 v[82:85], v148 offset:46592
	ds_read_b128 v[90:93], v148 offset:46624
	s_waitcnt lgkmcnt(1)
	v_mfma_f32_32x32x16_bf16 v[34:49], v[82:85], v[98:101], v[34:49]
	v_mfma_f32_32x32x16_bf16 v[66:81], v[86:89], v[102:105], v[66:81]
	ds_read_b128 v[82:85], v148 offset:40000
	ds_read_b128 v[86:89], v148 offset:40032
	s_waitcnt lgkmcnt(2)
	v_mfma_f32_32x32x16_bf16 v[34:49], v[90:93], v[102:105], v[34:49]
	s_waitcnt lgkmcnt(1)
	v_mfma_f32_32x32x16_bf16 v[66:81], v[82:85], v[106:109], v[66:81]
	ds_read_b128 v[82:85], v148 offset:46656
	ds_read_b128 v[90:93], v148 offset:46688
	s_waitcnt lgkmcnt(1)
	v_mfma_f32_32x32x16_bf16 v[34:49], v[82:85], v[106:109], v[34:49]
	v_mfma_f32_32x32x16_bf16 v[66:81], v[86:89], v[110:113], v[66:81]
	ds_read_b128 v[82:85], v148 offset:40064
	ds_read_b128 v[86:89], v148 offset:40096
	s_waitcnt lgkmcnt(2)
	v_mfma_f32_32x32x16_bf16 v[34:49], v[90:93], v[110:113], v[34:49]
	s_waitcnt lgkmcnt(1)
	v_mfma_f32_32x32x16_bf16 v[66:81], v[82:85], v[114:117], v[66:81]
	ds_read_b128 v[82:85], v148 offset:46720
	ds_read_b128 v[90:93], v148 offset:46752
	s_waitcnt lgkmcnt(1)
	v_mfma_f32_32x32x16_bf16 v[34:49], v[82:85], v[114:117], v[34:49]
	v_add_f32_e32 v82, v164, v94
	v_mfma_f32_32x32x16_bf16 v[66:81], v[86:89], v[118:121], v[66:81]
	s_waitcnt lgkmcnt(0)
	v_mfma_f32_32x32x16_bf16 v[34:49], v[90:93], v[118:121], v[34:49]
	s_nop 15
	s_nop 7
	s_nop 0
	v_max3_f32 v83, v66, v67, v34
	v_max3_f32 v84, v68, v69, v35
	v_max3_f32 v83, v83, v36, v37
	v_max3_f32 v84, v84, v72, v73
	v_max3_f32 v83, v83, v70, v71
	v_max3_f32 v84, v84, v40, v41
	v_max3_f32 v83, v83, v38, v39
	v_max3_f32 v84, v84, v76, v77
	v_max3_f32 v83, v83, v74, v75
	v_max3_f32 v84, v84, v44, v45
	v_max3_f32 v83, v83, v42, v43
	v_max3_f32 v84, v84, v80, v81
	v_max3_f32 v83, v83, v78, v79
	v_max3_f32 v84, v84, v48, v49
	v_max3_f32 v83, v83, v46, v47
	v_max_f32_e32 v84, v84, v84
	v_max_f32_e32 v83, v83, v83
	v_max_f32_e32 v83, v83, v84
	v_cmp_lt_f32_e32 vcc, s59, v83
	s_cbranch_vccz .LBB0_631
; template <int DQK, int DV, bool BIAS> ...
;     ...
;         if (__any(mx > 8.f)) {
;             mx = fmaxf(mx, __shfl_xor(mx, 32));
;             const float dl = fmaxf(mx, 0.f); mhat += dl;
;             const float f = __builtin_amdgcn_exp2f(-dl);
; #pragma unroll
;             for (int r = 0; r < 16; ++r) { p0[r] -= dl; p1[r] -= dl; negm[r] = -mhat; }
;             l *= f;
; #pragma unroll
;             for (int d = 0; d < NDT; ++d)
; #pragma unroll
;                 for (int r = 0; r < 16; ++r) o[d][r] *= f;
;         }
	ds_bpermute_b32 v50, v168, v83
	s_waitcnt lgkmcnt(0)
	v_max3_f32 v52, v83, v50, 0
	v_exp_f32_e64 v54, -v52
	v_add_f32_e32 v153, v153, v52
	v_xor_b32_e32 v50, 0x80000000, v153
	v_pk_add_f32 v[66:67], v[66:67], v[52:53] op_sel_hi:[1,0] neg_lo:[0,1] neg_hi:[0,1]
	v_pk_add_f32 v[34:35], v[34:35], v[52:53] op_sel_hi:[1,0] neg_lo:[0,1] neg_hi:[0,1]
	v_pk_add_f32 v[68:69], v[68:69], v[52:53] op_sel_hi:[1,0] neg_lo:[0,1] neg_hi:[0,1]
	v_pk_add_f32 v[36:37], v[36:37], v[52:53] op_sel_hi:[1,0] neg_lo:[0,1] neg_hi:[0,1]
	v_pk_add_f32 v[70:71], v[70:71], v[52:53] op_sel_hi:[1,0] neg_lo:[0,1] neg_hi:[0,1]
	v_pk_add_f32 v[38:39], v[38:39], v[52:53] op_sel_hi:[1,0] neg_lo:[0,1] neg_hi:[0,1]
	v_pk_add_f32 v[72:73], v[72:73], v[52:53] op_sel_hi:[1,0] neg_lo:[0,1] neg_hi:[0,1]
	v_pk_add_f32 v[40:41], v[40:41], v[52:53] op_sel_hi:[1,0] neg_lo:[0,1] neg_hi:[0,1]
	v_pk_add_f32 v[74:75], v[74:75], v[52:53] op_sel_hi:[1,0] neg_lo:[0,1] neg_hi:[0,1]
	v_pk_add_f32 v[42:43], v[42:43], v[52:53] op_sel_hi:[1,0] neg_lo:[0,1] neg_hi:[0,1]
	v_pk_add_f32 v[76:77], v[76:77], v[52:53] op_sel_hi:[1,0] neg_lo:[0,1] neg_hi:[0,1]
	v_pk_add_f32 v[44:45], v[44:45], v[52:53] op_sel_hi:[1,0] neg_lo:[0,1] neg_hi:[0,1]
	v_pk_add_f32 v[78:79], v[78:79], v[52:53] op_sel_hi:[1,0] neg_lo:[0,1] neg_hi:[0,1]
	v_pk_add_f32 v[46:47], v[46:47], v[52:53] op_sel_hi:[1,0] neg_lo:[0,1] neg_hi:[0,1]
	v_pk_add_f32 v[80:81], v[80:81], v[52:53] op_sel_hi:[1,0] neg_lo:[0,1] neg_hi:[0,1]
	v_pk_add_f32 v[48:49], v[48:49], v[52:53] op_sel_hi:[1,0] neg_lo:[0,1] neg_hi:[0,1]
	v_pk_mul_f32 v[32:33], v[32:33], v[54:55] op_sel_hi:[1,0]
	v_pk_mul_f32 v[30:31], v[30:31], v[54:55] op_sel_hi:[1,0]
	v_pk_mul_f32 v[28:29], v[28:29], v[54:55] op_sel_hi:[1,0]
	v_pk_mul_f32 v[26:27], v[26:27], v[54:55] op_sel_hi:[1,0]
	v_pk_mul_f32 v[24:25], v[24:25], v[54:55] op_sel_hi:[1,0]
	v_pk_mul_f32 v[22:23], v[22:23], v[54:55] op_sel_hi:[1,0]
	v_pk_mul_f32 v[20:21], v[20:21], v[54:55] op_sel_hi:[1,0]
	v_pk_mul_f32 v[18:19], v[18:19], v[54:55] op_sel_hi:[1,0]
	v_pk_mul_f32 v[16:17], v[16:17], v[54:55] op_sel_hi:[1,0]
	v_pk_mul_f32 v[14:15], v[14:15], v[54:55] op_sel_hi:[1,0]
	v_pk_mul_f32 v[12:13], v[12:13], v[54:55] op_sel_hi:[1,0]
	v_pk_mul_f32 v[10:11], v[10:11], v[54:55] op_sel_hi:[1,0]
	v_pk_mul_f32 v[8:9], v[8:9], v[54:55] op_sel_hi:[1,0]
	v_pk_mul_f32 v[6:7], v[6:7], v[54:55] op_sel_hi:[1,0]
	v_pk_mul_f32 v[4:5], v[4:5], v[54:55] op_sel_hi:[1,0]
	v_pk_mul_f32 v[2:3], v[2:3], v[54:55] op_sel_hi:[1,0]
	v_mul_f32_e32 v82, v82, v54
	v_mov_b32_e32 v51, v50
	v_mov_b32_e32 v52, v50
	v_mov_b32_e32 v53, v50
	v_mov_b32_e32 v54, v50
	v_mov_b32_e32 v55, v50
	v_mov_b32_e32 v56, v50
	v_mov_b32_e32 v57, v50
	v_mov_b32_e32 v58, v50
	v_mov_b32_e32 v59, v50
	v_mov_b32_e32 v60, v50
	v_mov_b32_e32 v61, v50
	v_mov_b32_e32 v62, v50
	v_mov_b32_e32 v63, v50
	v_mov_b32_e32 v64, v50
	v_mov_b32_e32 v65, v50
	s_branch .LBB0_631
